# weight-conversion items (run in GEMM tails): their f32 reads and bf16 writes marked non-temporal so they do not evict the GEMM outputs from L2
# speedup vs baseline: 1.0195x; 1.0195x over previous
; __device__ __forceinline__ void tr_item(const float* __restrict__ W, int ldw, int k0, int n0, bf16* __restrict__ WT, int ldt, int drow, const float* __restrict__ mu, LAS float* scr, int lane, const float* __restrict__ gs = nullptr) {
; #pragma unroll 8
;     for (int i = 0; i < 32; ++i) { const int kk = 2 * i + (lane >> 5); scr[kk * 33 + (lane & 31)] = W[(size_t)(k0 + kk) * ldw + n0 + (lane & 31)]; }
;     asm volatile("s_waitcnt lgkmcnt(0)" ::: "memory");
.LBB0_1426:
	s_lshl_b32 s10, s5, 1
	s_lshl_b32 s11, s8, 1
	v_or_b32_e32 v41, s11, v14
	s_add_i32 s12, s10, 4
	s_add_i32 s13, s11, 4
	s_add_i32 s15, s11, 8
	v_add_u32_e32 v0, s4, v41
	v_or_b32_e32 v42, s12, v15
	v_or_b32_e32 v43, s13, v14
	v_mov_b32_e32 v7, v1
	v_or_b32_e32 v40, s10, v15
	s_add_i32 s17, s11, 12
	v_or_b32_e32 v45, s15, v14
	s_waitcnt lgkmcnt(3)
	v_lshlrev_b64 v[32:33], 12, v[0:1]
	v_add_u32_e32 v6, s7, v42
	v_add_u32_e32 v0, s4, v43
	v_mov_b32_e32 v5, v1
	s_add_i32 s14, s10, 8
	s_add_i32 s16, s10, 12
	s_add_i32 s19, s11, 16
	v_add_u32_e32 v4, s7, v40
	v_or_b32_e32 v47, s17, v14
	v_lshlrev_b64 v[6:7], 12, v[6:7]
	v_lshlrev_b64 v[34:35], 12, v[0:1]
	v_add_u32_e32 v0, s4, v45
	s_add_i32 s21, s11, 20
	v_or_b32_e32 v44, s14, v15
	v_or_b32_e32 v46, s16, v15
	v_or_b32_e32 v49, s19, v14
	v_lshlrev_b64 v[4:5], 12, v[4:5]
	v_lshl_add_u64 v[32:33], v[2:3], 0, v[32:33]
	v_lshl_add_u64 v[6:7], v[2:3], 0, v[6:7]
	v_lshlrev_b64 v[36:37], 12, v[0:1]
	v_add_u32_e32 v0, s4, v47
	v_mov_b32_e32 v9, v1
	v_mov_b32_e32 v11, v1
	s_add_i32 s18, s10, 16
	s_add_i32 s20, s10, 20
	s_add_i32 s23, s11, 24
	v_or_b32_e32 v51, s21, v14
	v_add_u32_e32 v8, s7, v44
	v_add_u32_e32 v10, s7, v46
	v_lshl_add_u64 v[4:5], v[2:3], 0, v[4:5]
	v_lshl_add_u64 v[34:35], v[2:3], 0, v[34:35]
	global_load_dword v56, v[32:33], off nt
	global_load_dword v57, v[4:5], off nt
	global_load_dword v58, v[34:35], off nt
	global_load_dword v59, v[6:7], off nt
	v_lshlrev_b64 v[6:7], 12, v[0:1]
	v_add_u32_e32 v0, s4, v49
	s_add_i32 s22, s10, 24
	s_add_i32 s10, s10, 28
	s_add_i32 s11, s11, 28
	v_or_b32_e32 v48, s18, v15
	v_or_b32_e32 v50, s20, v15
	v_or_b32_e32 v53, s23, v14
	v_lshlrev_b64 v[8:9], 12, v[8:9]
	v_lshlrev_b64 v[10:11], 12, v[10:11]
	v_lshl_add_u64 v[4:5], v[2:3], 0, v[36:37]
	v_lshl_add_u64 v[6:7], v[2:3], 0, v[6:7]
	v_lshlrev_b64 v[32:33], 12, v[0:1]
	v_add_u32_e32 v0, s4, v51
	s_waitcnt lgkmcnt(0)
	v_mov_b32_e32 v13, v1
	v_mov_b32_e32 v27, v1
	v_or_b32_e32 v52, s22, v15
	v_or_b32_e32 v54, s10, v15
	v_or_b32_e32 v55, s11, v14
	v_add_u32_e32 v12, s7, v48
	v_add_u32_e32 v26, s7, v50
	v_lshl_add_u64 v[8:9], v[2:3], 0, v[8:9]
	v_lshl_add_u64 v[10:11], v[2:3], 0, v[10:11]
	global_load_dword v60, v[4:5], off nt
	global_load_dword v61, v[8:9], off nt
	global_load_dword v62, v[6:7], off nt
	global_load_dword v63, v[10:11], off nt
	v_lshlrev_b64 v[6:7], 12, v[0:1]
	v_add_u32_e32 v0, s4, v53
	v_mov_b32_e32 v29, v1
	v_mov_b32_e32 v31, v1
	v_add_u32_e32 v28, s7, v52
	v_add_u32_e32 v30, s7, v54
	v_lshlrev_b64 v[12:13], 12, v[12:13]
	v_lshlrev_b64 v[26:27], 12, v[26:27]
	v_lshl_add_u64 v[4:5], v[2:3], 0, v[32:33]
	v_lshl_add_u64 v[6:7], v[2:3], 0, v[6:7]
	v_lshlrev_b64 v[8:9], 12, v[0:1]
	v_add_u32_e32 v0, s4, v55
	v_lshlrev_b64 v[28:29], 12, v[28:29]
	v_lshlrev_b64 v[30:31], 12, v[30:31]
	v_lshl_add_u64 v[12:13], v[2:3], 0, v[12:13]
	v_lshl_add_u64 v[26:27], v[2:3], 0, v[26:27]
	global_load_dword v64, v[4:5], off nt
	global_load_dword v65, v[12:13], off nt
	global_load_dword v66, v[6:7], off nt
	global_load_dword v67, v[26:27], off nt
	v_lshl_add_u64 v[4:5], v[2:3], 0, v[8:9]
	v_lshlrev_b64 v[6:7], 12, v[0:1]
	v_lshl_add_u64 v[28:29], v[2:3], 0, v[28:29]
	v_lshl_add_u64 v[30:31], v[2:3], 0, v[30:31]
	v_lshl_add_u64 v[6:7], v[2:3], 0, v[6:7]
	global_load_dword v0, v[4:5], off nt
	global_load_dword v68, v[28:29], off nt
	global_load_dword v69, v[6:7], off nt
	global_load_dword v70, v[30:31], off nt
	s_add_i32 s8, s8, 16
	s_add_i32 s5, s5, 16
	s_add_i32 s9, s9, -16
	v_mad_u64_u32 v[4:5], s[10:11], v41, s26, v[18:19]
	s_cmp_lg_u32 s9, 0
	v_mad_u64_u32 v[6:7], s[10:11], v40, s26, v[18:19]
	v_mad_u64_u32 v[8:9], s[10:11], v43, s26, v[18:19]
	v_mad_u64_u32 v[10:11], s[10:11], v42, s26, v[18:19]
	v_mad_u64_u32 v[12:13], s[10:11], v45, s26, v[18:19]
	v_mad_u64_u32 v[26:27], s[10:11], v44, s26, v[18:19]
	v_mad_u64_u32 v[28:29], s[10:11], v47, s26, v[18:19]
	v_mad_u64_u32 v[30:31], s[10:11], v46, s26, v[18:19]
	v_mad_u64_u32 v[32:33], s[10:11], v49, s26, v[18:19]
	v_mad_u64_u32 v[34:35], s[10:11], v48, s26, v[18:19]
	v_mad_u64_u32 v[36:37], s[10:11], v51, s26, v[18:19]
	v_mad_u64_u32 v[40:41], s[10:11], v50, s26, v[18:19]
	v_mad_u64_u32 v[42:43], s[10:11], v53, s26, v[18:19]
	v_mad_u64_u32 v[44:45], s[10:11], v52, s26, v[18:19]
	v_mad_u64_u32 v[46:47], s[10:11], v55, s26, v[18:19]
	v_mad_u64_u32 v[48:49], s[10:11], v54, s26, v[18:19]
	s_waitcnt vmcnt(15)
	ds_write_b32 v4, v56
	s_waitcnt vmcnt(14)
	ds_write_b32 v6, v57
	s_waitcnt vmcnt(13)
	ds_write_b32 v8, v58
	s_waitcnt vmcnt(12)
	ds_write_b32 v10, v59
	s_waitcnt vmcnt(11)
	ds_write_b32 v12, v60
	s_waitcnt vmcnt(10)
	ds_write_b32 v26, v61
	s_waitcnt vmcnt(9)
	ds_write_b32 v28, v62
	s_waitcnt vmcnt(8)
	ds_write_b32 v30, v63
	s_waitcnt vmcnt(7)
	ds_write_b32 v32, v64
	s_waitcnt vmcnt(6)
	ds_write_b32 v34, v65
	s_waitcnt vmcnt(5)
	ds_write_b32 v36, v66
	s_waitcnt vmcnt(4)
	ds_write_b32 v40, v67
	s_waitcnt vmcnt(3)
	ds_write_b32 v42, v0
	s_waitcnt vmcnt(2)
	ds_write_b32 v44, v68
	s_waitcnt vmcnt(1)
	ds_write_b32 v46, v69
	s_waitcnt vmcnt(0)
	ds_write_b32 v48, v70
	s_cbranch_scc1 .LBB0_1426
; #define LAS __attribute__((address_space(3)))
; __device__ __forceinline__ v4u pack8(const float (&f)[8]) { v4u w; w.x = cvt_pk_bf16(f[0], f[1]); w.y = cvt_pk_bf16(f[2], f[3]); w.z = cvt_pk_bf16(f[4], f[5]); w.w = cvt_pk_bf16(f[6], f[7]); return w; }
; __device__ __forceinline__ void tr_item(const float* __restrict__ W, int ldw, int k0, int n0, bf16* __restrict__ WT, int ldt, int drow, const float* __restrict__ mu, LAS float* scr, int lane, const float* __restrict__ gs = nullptr) {
;     ...
;     for (int j = 0; j < 4; ++j) {
;         const int n = (lane >> 3) + 8 * j; const LAS float* s = scr + (8 * c) * 33 + n;
;         float f[8];
; #pragma unroll
;         for (int e = 0; e < 8; ++e) f[e] = s[e * 33];
;         bf16* dp = WT + (size_t)(drow + n) * ldt + k0 + 8 * c;
;         if (mu) {
;             float f1[8], f2[8];
; #pragma unroll
;             for (int e = 0; e < 8; ++e) { f1[e] = f[e] * (1.f - mv[e]); f2[e] = f[e] * mv[e]; }
;             *(v4u*)dp = pack8(f1); *(v4u*)(dp + 1024) = pack8(f2);
;         } else { if (gs) {
; #pragma unroll
;             for (int e = 0; e < 8; ++e) f[e] *= mv[e]; }
;             *(v4u*)dp = pack8(f); }
; __device__ __forceinline__ void ph_p0(const Params& p, LAS unsigned char* lds, int tid, int lane, int wave) {
;     ...
;         { const int i = r / 1408, q = r % 1408, kb = q / 32, nb = q % 32;
;             tr_item(p.in[I_WD] + (size_t)i * DFF * D, D, 64 * kb, 32 * nb, (bf16*)(ws + WS_WD + i * SZ_WD), DFF, 32 * nb, nullptr, scr, lane); }
	s_mul_i32 s1, s1, 0x580000
	v_readlane_b32 s5, v252, 10
	s_add_u32 s1, s5, s1
	v_readlane_b32 s5, v252, 11
	s_addc_u32 s5, s5, 0
	s_lshl_b32 s4, s4, 1
	s_add_u32 s4, s1, s4
	s_addc_u32 s5, s5, 0
	v_lshlrev_b32_e32 v0, 1, v20
	s_waitcnt lgkmcnt(0)
	v_lshl_add_u64 v[6:7], s[4:5], 0, v[0:1]
	v_or_b32_e32 v0, s0, v17
	v_mul_u32_u24_e32 v0, 0xb00, v0
	ds_read2_b32 v[8:9], v19 offset0:33 offset1:41
	ds_read2_b32 v[10:11], v19 offset1:8
	ds_read2_b32 v[12:13], v19 offset0:66 offset1:74
	ds_read2_b32 v[26:27], v19 offset0:99 offset1:107
	ds_read2_b32 v[28:29], v19 offset0:132 offset1:140
	ds_read2_b32 v[30:31], v19 offset0:165 offset1:173
	ds_read2_b32 v[32:33], v19 offset0:198 offset1:206
	ds_read2_b32 v[34:35], v19 offset0:231 offset1:239
	v_lshlrev_b32_e32 v0, 1, v0
	v_lshl_add_u64 v[36:37], v[6:7], 0, v[0:1]
	v_or_b32_e32 v0, s0, v21
	v_mul_u32_u24_e32 v0, 0xb00, v0
	v_lshlrev_b32_e32 v0, 1, v0
	s_waitcnt lgkmcnt(6)
	v_cvt_pk_bf16_f32 v2, v10, v8
	s_waitcnt lgkmcnt(4)
	v_cvt_pk_bf16_f32 v3, v12, v26
	s_waitcnt lgkmcnt(2)
	v_cvt_pk_bf16_f32 v4, v28, v30
	s_waitcnt lgkmcnt(0)
	v_cvt_pk_bf16_f32 v5, v32, v34
	global_store_dwordx4 v[36:37], v[2:5], off nt
	v_lshl_add_u64 v[36:37], v[6:7], 0, v[0:1]
	v_or_b32_e32 v0, s0, v38
	v_cvt_pk_bf16_f32 v2, v11, v9
	v_cvt_pk_bf16_f32 v3, v13, v27
	v_cvt_pk_bf16_f32 v4, v29, v31
	v_cvt_pk_bf16_f32 v5, v33, v35
	global_store_dwordx4 v[36:37], v[2:5], off nt
	v_mul_u32_u24_e32 v0, 0xb00, v0
	ds_read2_b32 v[8:9], v19 offset0:16 offset1:24
	ds_read2_b32 v[10:11], v19 offset0:49 offset1:57
	ds_read2_b32 v[12:13], v19 offset0:82 offset1:90
	ds_read2_b32 v[26:27], v19 offset0:115 offset1:123
	ds_read2_b32 v[28:29], v19 offset0:148 offset1:156
	ds_read2_b32 v[30:31], v19 offset0:181 offset1:189
	ds_read2_b32 v[32:33], v19 offset0:214 offset1:222
	ds_read2_b32 v[34:35], v19 offset0:247 offset1:255
	v_lshlrev_b32_e32 v0, 1, v0
	v_lshl_add_u64 v[36:37], v[6:7], 0, v[0:1]
	v_or_b32_e32 v0, s0, v39
	v_mul_u32_u24_e32 v0, 0xb00, v0
	v_lshlrev_b32_e32 v0, 1, v0
	s_waitcnt lgkmcnt(6)
	v_cvt_pk_bf16_f32 v2, v8, v10
	s_waitcnt lgkmcnt(4)
	v_cvt_pk_bf16_f32 v3, v12, v26
	s_waitcnt lgkmcnt(2)
	v_cvt_pk_bf16_f32 v4, v28, v30
	s_waitcnt lgkmcnt(0)
	v_cvt_pk_bf16_f32 v5, v32, v34
	v_lshl_add_u64 v[6:7], v[6:7], 0, v[0:1]
	global_store_dwordx4 v[36:37], v[2:5], off nt
	s_mov_b64 s[0:1], 0
	s_nop 0
	v_cvt_pk_bf16_f32 v2, v9, v11
	v_cvt_pk_bf16_f32 v3, v13, v27
	v_cvt_pk_bf16_f32 v4, v29, v31
	v_cvt_pk_bf16_f32 v5, v33, v35
	global_store_dwordx4 v[6:7], v[2:5], off nt
	s_waitcnt lgkmcnt(0)

; __device__ __forceinline__ void tr_item(const float* __restrict__ W, int ldw, int k0, int n0, bf16* __restrict__ WT, int ldt, int drow, const float* __restrict__ mu, LAS float* scr, int lane, const float* __restrict__ gs = nullptr) {
; #pragma unroll 8
;     for (int i = 0; i < 32; ++i) { const int kk = 2 * i + (lane >> 5); scr[kk * 33 + (lane & 31)] = W[(size_t)(k0 + kk) * ldw + n0 + (lane & 31)]; }
;     asm volatile("s_waitcnt lgkmcnt(0)" ::: "memory");
;     const int c = lane & 7;
;     float mv[8];
;     if (mu) {
; #pragma unroll
;         for (int e = 0; e < 8; ++e) mv[e] = mu[k0 + 8 * c + e];
;     } else if (gs) {
; #pragma unroll
;         for (int e = 0; e < 8; ++e) mv[e] = gs[k0 + 8 * c + e];
;     }
.LBB0_1434:
	s_lshl_b32 s10, s7, 1
	s_lshl_b32 s11, s8, 1
	v_or_b32_e32 v0, s10, v15
	v_or_b32_e32 v50, s11, v14
	s_add_i32 s12, s10, 4
	s_add_i32 s13, s11, 4
	s_add_i32 s14, s10, 8
	s_add_i32 s15, s11, 8
	s_add_i32 s16, s10, 12
	s_add_i32 s17, s11, 12
	s_add_i32 s18, s10, 16
	s_add_i32 s19, s11, 16
	s_add_i32 s20, s10, 20
	s_add_i32 s21, s11, 20
	s_add_i32 s22, s10, 24
	s_add_i32 s23, s11, 24
	s_add_i32 s10, s10, 28
	s_add_i32 s11, s11, 28
	v_add_u32_e32 v4, s1, v50
	v_or_b32_e32 v51, s12, v15
	v_or_b32_e32 v52, s13, v14
	v_or_b32_e32 v53, s14, v15
	v_or_b32_e32 v54, s15, v14
	v_or_b32_e32 v55, s16, v15
	v_or_b32_e32 v56, s17, v14
	v_or_b32_e32 v57, s18, v15
	v_or_b32_e32 v58, s19, v14
	v_or_b32_e32 v59, s20, v15
	v_or_b32_e32 v60, s21, v14
	v_or_b32_e32 v61, s22, v15
	v_or_b32_e32 v62, s23, v14
	v_or_b32_e32 v63, s10, v15
	v_or_b32_e32 v64, s11, v14
	v_add_u32_e32 v6, s5, v0
	v_mad_u64_u32 v[4:5], s[10:11], v4, s25, v[2:3]
	v_add_u32_e32 v10, s5, v51
	v_add_u32_e32 v8, s1, v52
	v_add_u32_e32 v26, s5, v53
	s_waitcnt lgkmcnt(0)
	v_add_u32_e32 v12, s1, v54
	v_add_u32_e32 v30, s5, v55
	v_add_u32_e32 v28, s1, v56
	v_add_u32_e32 v34, s5, v57
	v_add_u32_e32 v32, s1, v58
	v_add_u32_e32 v40, s5, v59
	v_add_u32_e32 v36, s1, v60
	v_add_u32_e32 v44, s5, v61
	v_add_u32_e32 v42, s1, v62
	v_add_u32_e32 v48, s5, v63
	v_add_u32_e32 v46, s1, v64
	v_mad_u64_u32 v[6:7], s[10:11], v6, s25, v[2:3]
	v_mad_u64_u32 v[8:9], s[10:11], v8, s25, v[2:3]
	v_mad_u64_u32 v[10:11], s[10:11], v10, s25, v[2:3]
	v_mad_u64_u32 v[12:13], s[10:11], v12, s25, v[2:3]
	v_mad_u64_u32 v[26:27], s[10:11], v26, s25, v[2:3]
	v_mad_u64_u32 v[28:29], s[10:11], v28, s25, v[2:3]
	v_mad_u64_u32 v[30:31], s[10:11], v30, s25, v[2:3]
	v_mad_u64_u32 v[32:33], s[10:11], v32, s25, v[2:3]
	v_mad_u64_u32 v[34:35], s[10:11], v34, s25, v[2:3]
	v_mad_u64_u32 v[36:37], s[10:11], v36, s25, v[2:3]
	v_mad_u64_u32 v[40:41], s[10:11], v40, s25, v[2:3]
	v_mad_u64_u32 v[42:43], s[10:11], v42, s25, v[2:3]
	v_mad_u64_u32 v[44:45], s[10:11], v44, s25, v[2:3]
	v_mad_u64_u32 v[46:47], s[10:11], v46, s25, v[2:3]
	v_mad_u64_u32 v[48:49], s[10:11], v48, s25, v[2:3]
	global_load_dword v65, v[4:5], off nt
	global_load_dword v66, v[6:7], off nt
	global_load_dword v67, v[8:9], off nt
	global_load_dword v68, v[10:11], off nt
	global_load_dword v69, v[12:13], off nt
	global_load_dword v70, v[26:27], off nt
	global_load_dword v71, v[28:29], off nt
	global_load_dword v72, v[30:31], off nt
	global_load_dword v73, v[32:33], off nt
	global_load_dword v74, v[34:35], off nt
	global_load_dword v75, v[36:37], off nt
	global_load_dword v76, v[40:41], off nt
	global_load_dword v77, v[42:43], off nt
	global_load_dword v78, v[44:45], off nt
	global_load_dword v79, v[46:47], off nt
	global_load_dword v80, v[48:49], off nt
	s_add_i32 s8, s8, 16
	s_add_i32 s7, s7, 16
	s_add_i32 s9, s9, -16
	v_mad_u64_u32 v[4:5], s[10:11], v50, s26, v[18:19]
	s_cmp_lg_u32 s9, 0
	v_mad_u64_u32 v[6:7], s[10:11], v0, s26, v[18:19]
	v_mad_u64_u32 v[8:9], s[10:11], v52, s26, v[18:19]
	v_mad_u64_u32 v[10:11], s[10:11], v51, s26, v[18:19]
	v_mad_u64_u32 v[12:13], s[10:11], v54, s26, v[18:19]
	v_mad_u64_u32 v[26:27], s[10:11], v53, s26, v[18:19]
	v_mad_u64_u32 v[28:29], s[10:11], v56, s26, v[18:19]
	v_mad_u64_u32 v[30:31], s[10:11], v55, s26, v[18:19]
	v_mad_u64_u32 v[32:33], s[10:11], v58, s26, v[18:19]
	v_mad_u64_u32 v[34:35], s[10:11], v57, s26, v[18:19]
	v_mad_u64_u32 v[36:37], s[10:11], v60, s26, v[18:19]
	v_mad_u64_u32 v[40:41], s[10:11], v59, s26, v[18:19]
	v_mad_u64_u32 v[42:43], s[10:11], v62, s26, v[18:19]
	v_mad_u64_u32 v[44:45], s[10:11], v61, s26, v[18:19]
	v_mad_u64_u32 v[46:47], s[10:11], v64, s26, v[18:19]
	v_mad_u64_u32 v[48:49], s[10:11], v63, s26, v[18:19]
	s_waitcnt vmcnt(15)
	ds_write_b32 v4, v65
	s_waitcnt vmcnt(14)
	ds_write_b32 v6, v66
	s_waitcnt vmcnt(13)
	ds_write_b32 v8, v67
	s_waitcnt vmcnt(12)
	ds_write_b32 v10, v68
	s_waitcnt vmcnt(11)
	ds_write_b32 v12, v69
	s_waitcnt vmcnt(10)
	ds_write_b32 v26, v70
	s_waitcnt vmcnt(9)
	ds_write_b32 v28, v71
	s_waitcnt vmcnt(8)
	ds_write_b32 v30, v72
	s_waitcnt vmcnt(7)
	ds_write_b32 v32, v73
	s_waitcnt vmcnt(6)
	ds_write_b32 v34, v74
	s_waitcnt vmcnt(5)
	ds_write_b32 v36, v75
	s_waitcnt vmcnt(4)
	ds_write_b32 v40, v76
	s_waitcnt vmcnt(3)
	ds_write_b32 v42, v77
	s_waitcnt vmcnt(2)
	ds_write_b32 v44, v78
	s_waitcnt vmcnt(1)
	ds_write_b32 v46, v79
	s_waitcnt vmcnt(0)
	ds_write_b32 v48, v80
	s_cbranch_scc1 .LBB0_1434
	s_waitcnt lgkmcnt(0)
	v_readlane_b32 s8, v253, 12
	v_readlane_b32 s9, v253, 13
	v_mov_b32_e32 v4, 0
	s_andn2_b64 vcc, exec, s[8:9]
	v_mov_b32_e32 v5, 0
	v_mov_b32_e32 v6, 0
	v_mov_b32_e32 v7, 0
	v_mov_b32_e32 v8, 0
	v_mov_b32_e32 v9, 0
	v_mov_b32_e32 v2, 0
	v_mov_b32_e32 v3, 0
	v_mov_b32_e32 v10, 0
	v_mov_b32_e32 v11, 0
	s_cbranch_vccnz .LBB0_1437
	s_lshl_b32 s5, s0, 12
	s_add_u32 s8, s40, s5
	v_or_b32_e32 v0, s1, v20
	s_addc_u32 s9, s41, 0
	v_lshlrev_b32_e32 v0, 2, v0
	global_load_dwordx4 v[2:5], v0, s[8:9] offset:16
	global_load_dwordx4 v[6:9], v0, s[8:9]
	s_waitcnt vmcnt(1)
	v_mov_b32_e32 v10, v4
	v_mov_b32_e32 v11, v5
; #define LAS __attribute__((address_space(3)))
; __device__ __forceinline__ v4u pack8(const float (&f)[8]) { v4u w; w.x = cvt_pk_bf16(f[0], f[1]); w.y = cvt_pk_bf16(f[2], f[3]); w.z = cvt_pk_bf16(f[4], f[5]); w.w = cvt_pk_bf16(f[6], f[7]); return w; }
; __device__ __forceinline__ void tr_item(const float* __restrict__ W, int ldw, int k0, int n0, bf16* __restrict__ WT, int ldt, int drow, const float* __restrict__ mu, LAS float* scr, int lane, const float* __restrict__ gs = nullptr) {
;     ...
;     for (int j = 0; j < 4; ++j) {
;         const int n = (lane >> 3) + 8 * j; const LAS float* s = scr + (8 * c) * 33 + n;
;         float f[8];
; #pragma unroll
;         for (int e = 0; e < 8; ++e) f[e] = s[e * 33];
;         bf16* dp = WT + (size_t)(drow + n) * ldt + k0 + 8 * c;
;         if (mu) {
;             float f1[8], f2[8];
; #pragma unroll
;             for (int e = 0; e < 8; ++e) { f1[e] = f[e] * (1.f - mv[e]); f2[e] = f[e] * mv[e]; }
;             *(v4u*)dp = pack8(f1); *(v4u*)(dp + 1024) = pack8(f2);
;         } else { if (gs) {
; #pragma unroll
;             for (int e = 0; e < 8; ++e) f[e] *= mv[e]; }
;             *(v4u*)dp = pack8(f); }
; __device__ __forceinline__ void ph_p0(const Params& p, LAS unsigned char* lds, int tid, int lane, int wave) {
;     ...
;         if (r < C_WUG) { const int i = r / 2816, q = r % 2816, kb = q / 176, nb = q % 176, n0 = 32 * nb;
;             const int drow = n0 < DFF ? 256 * (n0 / 128) + (n0 % 128) : 256 * ((n0 - DFF) / 128) + 128 + ((n0 - DFF) % 128);
;             tr_item(p.in[I_WUG] + (size_t)i * D * 2 * DFF, 2 * DFF, 64 * kb, n0, (bf16*)(ws + WS_WUG + i * SZ_WUG), D, drow, nullptr, scr, lane, p.in[I_NFFN] + (size_t)i * D); continue; }
.LBB0_1437:
	s_mul_i32 s0, s0, 0xb00000
	v_readlane_b32 s5, v252, 12
	s_add_u32 s0, s5, s0
	v_readlane_b32 s5, v252, 13
	s_addc_u32 s5, s5, 0
	s_lshl_b32 s1, s1, 1
	ds_read2_b32 v[30:31], v19 offset0:33 offset1:41
	ds_read2_b32 v[32:33], v19 offset0:66 offset1:74
	ds_read2_b32 v[34:35], v19 offset0:99 offset1:107
	ds_read2_b32 v[36:37], v19 offset0:132 offset1:140
	ds_read2_b32 v[40:41], v19 offset0:165 offset1:173
	ds_read2_b32 v[42:43], v19 offset0:198 offset1:206
	ds_read2_b32 v[44:45], v19 offset1:8
	ds_read2_b32 v[46:47], v19 offset0:231 offset1:239
	s_add_u32 s0, s0, s1
	s_addc_u32 s1, s5, 0
	v_lshlrev_b32_e32 v0, 1, v20
	v_lshl_add_u64 v[12:13], s[0:1], 0, v[0:1]
	v_add_u32_e32 v0, s4, v17
	v_lshlrev_b64 v[26:27], 11, v[0:1]
	v_lshl_add_u64 v[48:49], v[12:13], 0, v[26:27]
	s_waitcnt lgkmcnt(1)
	v_mov_b32_e32 v26, v44
	v_mov_b32_e32 v27, v30
	v_mov_b32_e32 v28, v32
	v_mov_b32_e32 v29, v34
	v_mov_b32_e32 v52, v42
	s_waitcnt lgkmcnt(0)
	v_mov_b32_e32 v53, v46
	v_readlane_b32 s0, v253, 10
	s_waitcnt vmcnt(0)
	v_pk_mul_f32 v[26:27], v[26:27], v[6:7]
	v_pk_mul_f32 v[28:29], v[8:9], v[28:29]
	v_mov_b32_e32 v50, v36
	v_mov_b32_e32 v51, v40
	v_pk_mul_f32 v[4:5], v[4:5], v[52:53]
	v_readlane_b32 s1, v253, 11
	v_pk_mul_f32 v[50:51], v[2:3], v[50:51]
	s_nop 0
	v_cndmask_b32_e64 v0, v4, v42, s[0:1]
	v_cndmask_b32_e64 v28, v28, v32, s[0:1]
	v_cndmask_b32_e64 v29, v29, v34, s[0:1]
	v_cndmask_b32_e64 v26, v26, v44, s[0:1]
	v_cndmask_b32_e64 v27, v27, v30, s[0:1]
	v_cndmask_b32_e64 v4, v5, v46, s[0:1]
	v_cndmask_b32_e64 v5, v50, v36, s[0:1]
	v_cndmask_b32_e64 v36, v51, v40, s[0:1]
	v_cvt_pk_bf16_f32 v26, v26, v27
	v_cvt_pk_bf16_f32 v27, v28, v29
	v_cvt_pk_bf16_f32 v28, v5, v36
	v_cvt_pk_bf16_f32 v29, v0, v4
	v_add_u32_e32 v0, s4, v21
	v_mov_b32_e32 v30, v45
	v_mov_b32_e32 v34, v33
	global_store_dwordx4 v[48:49], v[26:29], off nt
	v_lshlrev_b64 v[4:5], 11, v[0:1]
	v_mov_b32_e32 v40, v37
	v_pk_mul_f32 v[26:27], v[6:7], v[30:31]
	v_pk_mul_f32 v[28:29], v[8:9], v[34:35]
	v_mov_b32_e32 v46, v43
	v_lshl_add_u64 v[4:5], v[12:13], 0, v[4:5]
	v_pk_mul_f32 v[48:49], v[2:3], v[40:41]
	v_pk_mul_f32 v[50:51], v[10:11], v[46:47]
	v_cndmask_b32_e64 v28, v28, v33, s[0:1]
	v_cndmask_b32_e64 v29, v29, v35, s[0:1]
	v_cndmask_b32_e64 v26, v26, v45, s[0:1]
	v_cndmask_b32_e64 v27, v27, v31, s[0:1]
	v_cndmask_b32_e64 v0, v50, v43, s[0:1]
	v_cndmask_b32_e64 v30, v51, v47, s[0:1]
	v_cndmask_b32_e64 v32, v48, v37, s[0:1]
	v_cndmask_b32_e64 v34, v49, v41, s[0:1]
	v_cvt_pk_bf16_f32 v26, v26, v27
	v_cvt_pk_bf16_f32 v27, v28, v29
	v_cvt_pk_bf16_f32 v28, v32, v34
	v_cvt_pk_bf16_f32 v29, v0, v30
	global_store_dwordx4 v[4:5], v[26:29], off nt
	ds_read2_b32 v[4:5], v19 offset0:16 offset1:24
	ds_read2_b32 v[30:31], v19 offset0:49 offset1:57
	ds_read2_b32 v[32:33], v19 offset0:82 offset1:90
	ds_read2_b32 v[34:35], v19 offset0:115 offset1:123
	ds_read2_b32 v[36:37], v19 offset0:148 offset1:156
	ds_read2_b32 v[40:41], v19 offset0:181 offset1:189
	ds_read2_b32 v[42:43], v19 offset0:214 offset1:222
	ds_read2_b32 v[44:45], v19 offset0:247 offset1:255
	v_add_u32_e32 v0, s4, v38
	v_lshlrev_b64 v[26:27], 11, v[0:1]
	v_lshl_add_u64 v[46:47], v[12:13], 0, v[26:27]
	s_waitcnt lgkmcnt(7)
	v_mov_b32_e32 v26, v4
	s_waitcnt lgkmcnt(6)
	v_mov_b32_e32 v27, v30
	s_waitcnt lgkmcnt(5)
	v_mov_b32_e32 v28, v32
	s_waitcnt lgkmcnt(4)
	v_mov_b32_e32 v29, v34
	s_waitcnt lgkmcnt(3)
	v_mov_b32_e32 v48, v36
	s_waitcnt lgkmcnt(2)
	v_mov_b32_e32 v49, v40
	s_waitcnt lgkmcnt(1)
	v_mov_b32_e32 v50, v42
	s_waitcnt lgkmcnt(0)
	v_mov_b32_e32 v51, v44
	v_pk_mul_f32 v[26:27], v[6:7], v[26:27]
	v_pk_mul_f32 v[28:29], v[8:9], v[28:29]
	v_pk_mul_f32 v[48:49], v[2:3], v[48:49]
	v_pk_mul_f32 v[50:51], v[10:11], v[50:51]
	v_cndmask_b32_e64 v40, v49, v40, s[0:1]
	v_cndmask_b32_e64 v0, v50, v42, s[0:1]
	v_cndmask_b32_e64 v28, v28, v32, s[0:1]
	v_cndmask_b32_e64 v29, v29, v34, s[0:1]
	v_cndmask_b32_e64 v4, v26, v4, s[0:1]
	v_cndmask_b32_e64 v26, v27, v30, s[0:1]
	v_cndmask_b32_e64 v42, v51, v44, s[0:1]
	v_cndmask_b32_e64 v36, v48, v36, s[0:1]
	v_cvt_pk_bf16_f32 v26, v4, v26
	v_cvt_pk_bf16_f32 v27, v28, v29
	v_cvt_pk_bf16_f32 v28, v36, v40
	v_cvt_pk_bf16_f32 v29, v0, v42
	v_add_u32_e32 v0, s4, v39
	v_mov_b32_e32 v30, v5
	v_mov_b32_e32 v34, v33
	v_mov_b32_e32 v40, v37
	v_mov_b32_e32 v44, v43
	global_store_dwordx4 v[46:47], v[26:29], off nt
	v_pk_mul_f32 v[6:7], v[6:7], v[30:31]
	v_pk_mul_f32 v[8:9], v[8:9], v[34:35]
	v_lshlrev_b64 v[26:27], 11, v[0:1]
	v_pk_mul_f32 v[2:3], v[2:3], v[40:41]
	v_pk_mul_f32 v[10:11], v[10:11], v[44:45]
	v_lshl_add_u64 v[12:13], v[12:13], 0, v[26:27]
	v_cndmask_b32_e64 v0, v10, v43, s[0:1]
	v_cndmask_b32_e64 v10, v11, v45, s[0:1]
	v_cndmask_b32_e64 v4, v2, v37, s[0:1]
	v_cndmask_b32_e64 v11, v3, v41, s[0:1]
	v_cndmask_b32_e64 v3, v8, v33, s[0:1]
	v_cndmask_b32_e64 v2, v6, v5, s[0:1]
	v_cndmask_b32_e64 v5, v7, v31, s[0:1]
	v_cndmask_b32_e64 v8, v9, v35, s[0:1]
	v_cvt_pk_bf16_f32 v2, v2, v5
	v_cvt_pk_bf16_f32 v3, v3, v8
	v_cvt_pk_bf16_f32 v4, v4, v11
	v_cvt_pk_bf16_f32 v5, v0, v10
	global_store_dwordx4 v[12:13], v[2:5], off nt
	s_waitcnt lgkmcnt(0)
	s_mov_b64 s[0:1], 0

; __device__ __forceinline__ void tr_item(const float* __restrict__ W, int ldw, int k0, int n0, bf16* __restrict__ WT, int ldt, int drow, const float* __restrict__ mu, LAS float* scr, int lane, const float* __restrict__ gs = nullptr) {
; #pragma unroll 8
;     for (int i = 0; i < 32; ++i) { const int kk = 2 * i + (lane >> 5); scr[kk * 33 + (lane & 31)] = W[(size_t)(k0 + kk) * ldw + n0 + (lane & 31)]; }
;     asm volatile("s_waitcnt lgkmcnt(0)" ::: "memory");
.LBB0_1440:
	s_lshl_b32 s9, s4, 1
	s_lshl_b32 s10, s7, 1
	v_or_b32_e32 v41, s10, v14
	s_add_i32 s11, s9, 4
	s_add_i32 s12, s10, 4
	s_add_i32 s14, s10, 8
	v_add_u32_e32 v0, s1, v41
	v_or_b32_e32 v42, s11, v15
	v_or_b32_e32 v43, s12, v14
	v_mov_b32_e32 v7, v1
	v_or_b32_e32 v40, s9, v15
	s_add_i32 s16, s10, 12
	v_or_b32_e32 v45, s14, v14
	s_waitcnt lgkmcnt(3)
	v_lshlrev_b64 v[32:33], 12, v[0:1]
	v_add_u32_e32 v6, s5, v42
	v_add_u32_e32 v0, s1, v43
	v_mov_b32_e32 v5, v1
	s_add_i32 s13, s9, 8
	s_add_i32 s15, s9, 12
	s_add_i32 s18, s10, 16
	v_add_u32_e32 v4, s5, v40
	v_or_b32_e32 v47, s16, v14
	v_lshlrev_b64 v[6:7], 12, v[6:7]
	v_lshlrev_b64 v[34:35], 12, v[0:1]
	v_add_u32_e32 v0, s1, v45
	s_add_i32 s20, s10, 20
	v_or_b32_e32 v44, s13, v15
	v_or_b32_e32 v46, s15, v15
	v_or_b32_e32 v49, s18, v14
	v_lshlrev_b64 v[4:5], 12, v[4:5]
	v_lshl_add_u64 v[32:33], v[2:3], 0, v[32:33]
	v_lshl_add_u64 v[6:7], v[2:3], 0, v[6:7]
	v_lshlrev_b64 v[36:37], 12, v[0:1]
	v_add_u32_e32 v0, s1, v47
	v_mov_b32_e32 v9, v1
	v_mov_b32_e32 v11, v1
	s_add_i32 s17, s9, 16
	s_add_i32 s19, s9, 20
	s_add_i32 s22, s10, 24
	v_or_b32_e32 v51, s20, v14
	v_add_u32_e32 v8, s5, v44
	v_add_u32_e32 v10, s5, v46
	v_lshl_add_u64 v[4:5], v[2:3], 0, v[4:5]
	v_lshl_add_u64 v[34:35], v[2:3], 0, v[34:35]
	global_load_dword v56, v[32:33], off nt
	global_load_dword v57, v[4:5], off nt
	global_load_dword v58, v[34:35], off nt
	global_load_dword v59, v[6:7], off nt
	v_lshlrev_b64 v[6:7], 12, v[0:1]
	v_add_u32_e32 v0, s1, v49
	s_add_i32 s21, s9, 24
	s_add_i32 s9, s9, 28
	s_add_i32 s10, s10, 28
	v_or_b32_e32 v48, s17, v15
	v_or_b32_e32 v50, s19, v15
	v_or_b32_e32 v53, s22, v14
	v_lshlrev_b64 v[8:9], 12, v[8:9]
	v_lshlrev_b64 v[10:11], 12, v[10:11]
	v_lshl_add_u64 v[4:5], v[2:3], 0, v[36:37]
	v_lshl_add_u64 v[6:7], v[2:3], 0, v[6:7]
	v_lshlrev_b64 v[32:33], 12, v[0:1]
	v_add_u32_e32 v0, s1, v51
	s_waitcnt lgkmcnt(0)
	v_mov_b32_e32 v13, v1
	v_mov_b32_e32 v27, v1
	v_or_b32_e32 v52, s21, v15
	v_or_b32_e32 v54, s9, v15
	v_or_b32_e32 v55, s10, v14
	v_add_u32_e32 v12, s5, v48
	v_add_u32_e32 v26, s5, v50
	v_lshl_add_u64 v[8:9], v[2:3], 0, v[8:9]
	v_lshl_add_u64 v[10:11], v[2:3], 0, v[10:11]
	global_load_dword v60, v[4:5], off nt
	global_load_dword v61, v[8:9], off nt
	global_load_dword v62, v[6:7], off nt
	global_load_dword v63, v[10:11], off nt
	v_lshlrev_b64 v[6:7], 12, v[0:1]
	v_add_u32_e32 v0, s1, v53
	v_mov_b32_e32 v29, v1
	v_mov_b32_e32 v31, v1
	v_add_u32_e32 v28, s5, v52
	v_add_u32_e32 v30, s5, v54
	v_lshlrev_b64 v[12:13], 12, v[12:13]
	v_lshlrev_b64 v[26:27], 12, v[26:27]
	v_lshl_add_u64 v[4:5], v[2:3], 0, v[32:33]
	v_lshl_add_u64 v[6:7], v[2:3], 0, v[6:7]
	v_lshlrev_b64 v[8:9], 12, v[0:1]
	v_add_u32_e32 v0, s1, v55
	v_lshlrev_b64 v[28:29], 12, v[28:29]
	v_lshlrev_b64 v[30:31], 12, v[30:31]
	v_lshl_add_u64 v[12:13], v[2:3], 0, v[12:13]
	v_lshl_add_u64 v[26:27], v[2:3], 0, v[26:27]
	global_load_dword v64, v[4:5], off nt
	global_load_dword v65, v[12:13], off nt
	global_load_dword v66, v[6:7], off nt
	global_load_dword v67, v[26:27], off nt
	v_lshl_add_u64 v[4:5], v[2:3], 0, v[8:9]
	v_lshlrev_b64 v[6:7], 12, v[0:1]
	v_lshl_add_u64 v[28:29], v[2:3], 0, v[28:29]
	v_lshl_add_u64 v[30:31], v[2:3], 0, v[30:31]
	v_lshl_add_u64 v[6:7], v[2:3], 0, v[6:7]
	global_load_dword v0, v[4:5], off nt
	global_load_dword v68, v[28:29], off nt
	global_load_dword v69, v[6:7], off nt
	global_load_dword v70, v[30:31], off nt
	s_add_i32 s7, s7, 16
	s_add_i32 s4, s4, 16
	s_add_i32 s8, s8, -16
	v_mad_u64_u32 v[4:5], s[10:11], v41, s26, v[18:19]
	s_cmp_lg_u32 s8, 0
	v_mad_u64_u32 v[6:7], s[10:11], v40, s26, v[18:19]
	v_mad_u64_u32 v[8:9], s[10:11], v43, s26, v[18:19]
	v_mad_u64_u32 v[10:11], s[10:11], v42, s26, v[18:19]
	v_mad_u64_u32 v[12:13], s[10:11], v45, s26, v[18:19]
	v_mad_u64_u32 v[26:27], s[10:11], v44, s26, v[18:19]
	v_mad_u64_u32 v[28:29], s[10:11], v47, s26, v[18:19]
	v_mad_u64_u32 v[30:31], s[10:11], v46, s26, v[18:19]
	v_mad_u64_u32 v[32:33], s[10:11], v49, s26, v[18:19]
	v_mad_u64_u32 v[34:35], s[10:11], v48, s26, v[18:19]
	v_mad_u64_u32 v[36:37], s[10:11], v51, s26, v[18:19]
	v_mad_u64_u32 v[40:41], s[10:11], v50, s26, v[18:19]
	v_mad_u64_u32 v[42:43], s[10:11], v53, s26, v[18:19]
	v_mad_u64_u32 v[44:45], s[10:11], v52, s26, v[18:19]
	v_mad_u64_u32 v[46:47], s[10:11], v55, s26, v[18:19]
	v_mad_u64_u32 v[48:49], s[10:11], v54, s26, v[18:19]
	s_waitcnt vmcnt(15)
	ds_write_b32 v4, v56
	s_waitcnt vmcnt(14)
	ds_write_b32 v6, v57
	s_waitcnt vmcnt(13)
	ds_write_b32 v8, v58
	s_waitcnt vmcnt(12)
	ds_write_b32 v10, v59
	s_waitcnt vmcnt(11)
	ds_write_b32 v12, v60
	s_waitcnt vmcnt(10)
	ds_write_b32 v26, v61
	s_waitcnt vmcnt(9)
	ds_write_b32 v28, v62
	s_waitcnt vmcnt(8)
	ds_write_b32 v30, v63
	s_waitcnt vmcnt(7)
	ds_write_b32 v32, v64
	s_waitcnt vmcnt(6)
	ds_write_b32 v34, v65
	s_waitcnt vmcnt(5)
	ds_write_b32 v36, v66
	s_waitcnt vmcnt(4)
	ds_write_b32 v40, v67
	s_waitcnt vmcnt(3)
	ds_write_b32 v42, v0
	s_waitcnt vmcnt(2)
	ds_write_b32 v44, v68
	s_waitcnt vmcnt(1)
	ds_write_b32 v46, v69
	s_waitcnt vmcnt(0)
	ds_write_b32 v48, v70
	s_cbranch_scc1 .LBB0_1440
; #define LAS __attribute__((address_space(3)))
; __device__ __forceinline__ v4u pack8(const float (&f)[8]) { v4u w; w.x = cvt_pk_bf16(f[0], f[1]); w.y = cvt_pk_bf16(f[2], f[3]); w.z = cvt_pk_bf16(f[4], f[5]); w.w = cvt_pk_bf16(f[6], f[7]); return w; }
; __device__ __forceinline__ void tr_item(const float* __restrict__ W, int ldw, int k0, int n0, bf16* __restrict__ WT, int ldt, int drow, const float* __restrict__ mu, LAS float* scr, int lane, const float* __restrict__ gs = nullptr) {
;     ...
;     for (int j = 0; j < 4; ++j) {
;         const int n = (lane >> 3) + 8 * j; const LAS float* s = scr + (8 * c) * 33 + n;
;         float f[8];
; #pragma unroll
;         for (int e = 0; e < 8; ++e) f[e] = s[e * 33];
;         bf16* dp = WT + (size_t)(drow + n) * ldt + k0 + 8 * c;
;         if (mu) {
;             float f1[8], f2[8];
; #pragma unroll
;             for (int e = 0; e < 8; ++e) { f1[e] = f[e] * (1.f - mv[e]); f2[e] = f[e] * mv[e]; }
;             *(v4u*)dp = pack8(f1); *(v4u*)(dp + 1024) = pack8(f2);
;         } else { if (gs) {
; #pragma unroll
;             for (int e = 0; e < 8; ++e) f[e] *= mv[e]; }
;             *(v4u*)dp = pack8(f); }
; __device__ __forceinline__ void ph_p0(const Params& p, LAS unsigned char* lds, int tid, int lane, int wave) {
;     ...
;         if (r < C_WO) { const int j = r / 512, q = r % 512, kb = q / 32, nb = q % 32;
;             tr_item(p.in[I_WO] + (size_t)j * D * D, D, 64 * kb, 32 * nb, (bf16*)(ws + WS_WO + j * SZ_WO), D, 32 * nb, nullptr, scr, lane); continue; }
	s_lshl_b64 s[4:5], s[94:95], 21
	v_readlane_b32 s7, v252, 14
	s_add_u32 s4, s7, s4
	v_readlane_b32 s7, v252, 15
	s_addc_u32 s5, s7, s5
	s_lshl_b32 s1, s1, 1
	s_waitcnt lgkmcnt(0)
	s_add_u32 s4, s4, s1
	s_addc_u32 s5, s5, 0
	v_lshlrev_b32_e32 v0, 1, v20
	ds_read2_b32 v[8:9], v19 offset0:33 offset1:41
	ds_read2_b32 v[10:11], v19 offset1:8
	ds_read2_b32 v[12:13], v19 offset0:66 offset1:74
	ds_read2_b32 v[26:27], v19 offset0:99 offset1:107
	ds_read2_b32 v[28:29], v19 offset0:132 offset1:140
	ds_read2_b32 v[30:31], v19 offset0:165 offset1:173
	ds_read2_b32 v[32:33], v19 offset0:198 offset1:206
	ds_read2_b32 v[34:35], v19 offset0:231 offset1:239
	v_lshl_add_u64 v[6:7], s[4:5], 0, v[0:1]
	v_or_b32_e32 v0, s0, v17
	v_lshlrev_b32_e32 v0, 11, v0
	v_lshl_add_u64 v[36:37], v[6:7], 0, v[0:1]
	v_or_b32_e32 v0, s0, v21
	v_lshlrev_b32_e32 v0, 11, v0
	s_waitcnt lgkmcnt(6)
	v_cvt_pk_bf16_f32 v2, v10, v8
	s_waitcnt lgkmcnt(4)
	v_cvt_pk_bf16_f32 v3, v12, v26
	s_waitcnt lgkmcnt(2)
	v_cvt_pk_bf16_f32 v4, v28, v30
	s_waitcnt lgkmcnt(0)
	v_cvt_pk_bf16_f32 v5, v32, v34
	global_store_dwordx4 v[36:37], v[2:5], off nt
	v_lshl_add_u64 v[36:37], v[6:7], 0, v[0:1]
	v_or_b32_e32 v0, s0, v38
	v_cvt_pk_bf16_f32 v2, v11, v9
	v_cvt_pk_bf16_f32 v3, v13, v27
	v_cvt_pk_bf16_f32 v4, v29, v31
	v_cvt_pk_bf16_f32 v5, v33, v35
	global_store_dwordx4 v[36:37], v[2:5], off nt
	ds_read2_b32 v[8:9], v19 offset0:16 offset1:24
	ds_read2_b32 v[10:11], v19 offset0:49 offset1:57
	ds_read2_b32 v[12:13], v19 offset0:82 offset1:90
	ds_read2_b32 v[26:27], v19 offset0:115 offset1:123
	ds_read2_b32 v[28:29], v19 offset0:148 offset1:156
	ds_read2_b32 v[30:31], v19 offset0:181 offset1:189
	ds_read2_b32 v[32:33], v19 offset0:214 offset1:222
	ds_read2_b32 v[34:35], v19 offset0:247 offset1:255
	v_lshlrev_b32_e32 v0, 11, v0
	v_lshl_add_u64 v[36:37], v[6:7], 0, v[0:1]
	v_or_b32_e32 v0, s0, v39
	v_lshlrev_b32_e32 v0, 11, v0
	s_waitcnt lgkmcnt(6)
	v_cvt_pk_bf16_f32 v2, v8, v10
	s_waitcnt lgkmcnt(4)
	v_cvt_pk_bf16_f32 v3, v12, v26
	s_waitcnt lgkmcnt(2)
	v_cvt_pk_bf16_f32 v4, v28, v30
	s_waitcnt lgkmcnt(0)
	v_cvt_pk_bf16_f32 v5, v32, v34
	v_lshl_add_u64 v[6:7], v[6:7], 0, v[0:1]
	global_store_dwordx4 v[36:37], v[2:5], off nt
	s_nop 1
	v_cvt_pk_bf16_f32 v2, v9, v11
	v_cvt_pk_bf16_f32 v3, v13, v27
	v_cvt_pk_bf16_f32 v4, v29, v31
	v_cvt_pk_bf16_f32 v5, v33, v35
	global_store_dwordx4 v[6:7], v[2:5], off nt
	s_waitcnt lgkmcnt(0)

; __device__ __forceinline__ void tr_item(const float* __restrict__ W, int ldw, int k0, int n0, bf16* __restrict__ WT, int ldt, int drow, const float* __restrict__ mu, LAS float* scr, int lane, const float* __restrict__ gs = nullptr) {
; #pragma unroll 8
;     for (int i = 0; i < 32; ++i) { const int kk = 2 * i + (lane >> 5); scr[kk * 33 + (lane & 31)] = W[(size_t)(k0 + kk) * ldw + n0 + (lane & 31)]; }
;     asm volatile("s_waitcnt lgkmcnt(0)" ::: "memory");
; __device__ __forceinline__ void ph_p0(const Params& p, LAS unsigned char* lds, int tid, int lane, int wave) {
;     ...
;         if (r < C_V1) { const int kb = r;
;             tr_item(p.in[I_V1], LV, 64 * kb, 0, (bf16*)(ws + WS_WRW + 1 * SZ_WRW), KRW, 3360, p.in[I_MU] + (size_t)(1 * 6 + 3) * D, scr, lane); continue; }
.LBB0_1445:
	s_lshl_b32 s8, s4, 1
	s_lshl_b32 s9, s5, 1
	v_or_b32_e32 v0, s8, v15
	v_or_b32_e32 v48, s9, v14
	s_add_i32 s10, s8, 4
	s_add_i32 s11, s9, 4
	s_add_i32 s12, s8, 8
	s_add_i32 s13, s9, 8
	s_add_i32 s14, s8, 12
	s_add_i32 s15, s9, 12
	s_add_i32 s16, s8, 16
	s_add_i32 s17, s9, 16
	s_add_i32 s18, s8, 20
	s_add_i32 s19, s9, 20
	s_add_i32 s20, s8, 24
	s_add_i32 s21, s9, 24
	s_add_i32 s8, s8, 28
	s_add_i32 s9, s9, 28
	v_add_u32_e32 v4, s0, v48
	v_or_b32_e32 v49, s10, v15
	v_or_b32_e32 v50, s11, v14
	v_or_b32_e32 v51, s12, v15
	v_or_b32_e32 v52, s13, v14
	v_or_b32_e32 v53, s14, v15
	v_or_b32_e32 v54, s15, v14
	v_or_b32_e32 v55, s16, v15
	v_or_b32_e32 v56, s17, v14
	v_or_b32_e32 v57, s18, v15
	v_or_b32_e32 v58, s19, v14
	v_or_b32_e32 v59, s20, v15
	v_or_b32_e32 v60, s21, v14
	v_or_b32_e32 v61, s8, v15
	v_or_b32_e32 v62, s9, v14
	v_add_u32_e32 v2, s1, v0
	v_ashrrev_i32_e32 v5, 31, v4
	v_add_u32_e32 v6, s1, v49
	v_add_u32_e32 v8, s0, v50
	v_add_u32_e32 v10, s1, v51
	s_waitcnt lgkmcnt(0)
	v_add_u32_e32 v12, s0, v52
	v_add_u32_e32 v26, s1, v53
	v_add_u32_e32 v28, s0, v54
	v_add_u32_e32 v30, s1, v55
	v_add_u32_e32 v32, s0, v56
	v_add_u32_e32 v34, s1, v57
	v_add_u32_e32 v36, s0, v58
	v_add_u32_e32 v40, s1, v59
	v_add_u32_e32 v42, s0, v60
	v_add_u32_e32 v44, s1, v61
	v_add_u32_e32 v46, s0, v62
	v_ashrrev_i32_e32 v3, 31, v2
	v_lshlrev_b64 v[4:5], 7, v[4:5]
	v_ashrrev_i32_e32 v9, 31, v8
	v_ashrrev_i32_e32 v7, 31, v6
	v_ashrrev_i32_e32 v13, 31, v12
	v_ashrrev_i32_e32 v11, 31, v10
	v_ashrrev_i32_e32 v29, 31, v28
	v_ashrrev_i32_e32 v27, 31, v26
	v_ashrrev_i32_e32 v33, 31, v32
	v_ashrrev_i32_e32 v31, 31, v30
	v_ashrrev_i32_e32 v37, 31, v36
	v_ashrrev_i32_e32 v35, 31, v34
	v_ashrrev_i32_e32 v43, 31, v42
	v_ashrrev_i32_e32 v41, 31, v40
	v_ashrrev_i32_e32 v47, 31, v46
	v_ashrrev_i32_e32 v45, 31, v44
	v_lshlrev_b64 v[2:3], 7, v[2:3]
	v_lshl_add_u64 v[4:5], v[24:25], 0, v[4:5]
	v_lshlrev_b64 v[6:7], 7, v[6:7]
	v_lshlrev_b64 v[8:9], 7, v[8:9]
	v_lshlrev_b64 v[10:11], 7, v[10:11]
	v_lshlrev_b64 v[12:13], 7, v[12:13]
	v_lshlrev_b64 v[26:27], 7, v[26:27]
	v_lshlrev_b64 v[28:29], 7, v[28:29]
	v_lshlrev_b64 v[30:31], 7, v[30:31]
	v_lshlrev_b64 v[32:33], 7, v[32:33]
	v_lshlrev_b64 v[34:35], 7, v[34:35]
	v_lshlrev_b64 v[36:37], 7, v[36:37]
	v_lshlrev_b64 v[40:41], 7, v[40:41]
	v_lshlrev_b64 v[42:43], 7, v[42:43]
	v_lshlrev_b64 v[44:45], 7, v[44:45]
	v_lshlrev_b64 v[46:47], 7, v[46:47]
	v_lshl_add_u64 v[2:3], v[24:25], 0, v[2:3]
	v_lshl_add_u64 v[8:9], v[24:25], 0, v[8:9]
	v_lshl_add_u64 v[6:7], v[24:25], 0, v[6:7]
	v_lshl_add_u64 v[12:13], v[24:25], 0, v[12:13]
	v_lshl_add_u64 v[10:11], v[24:25], 0, v[10:11]
	v_lshl_add_u64 v[28:29], v[24:25], 0, v[28:29]
	v_lshl_add_u64 v[26:27], v[24:25], 0, v[26:27]
	v_lshl_add_u64 v[32:33], v[24:25], 0, v[32:33]
	v_lshl_add_u64 v[30:31], v[24:25], 0, v[30:31]
	v_lshl_add_u64 v[36:37], v[24:25], 0, v[36:37]
	v_lshl_add_u64 v[34:35], v[24:25], 0, v[34:35]
	v_lshl_add_u64 v[42:43], v[24:25], 0, v[42:43]
	v_lshl_add_u64 v[40:41], v[24:25], 0, v[40:41]
	v_lshl_add_u64 v[46:47], v[24:25], 0, v[46:47]
	v_lshl_add_u64 v[44:45], v[24:25], 0, v[44:45]
	global_load_dword v63, v[4:5], off nt
	global_load_dword v64, v[2:3], off nt
	global_load_dword v65, v[8:9], off nt
	global_load_dword v66, v[6:7], off nt
	global_load_dword v67, v[12:13], off nt
	global_load_dword v68, v[10:11], off nt
	global_load_dword v69, v[28:29], off nt
	global_load_dword v70, v[26:27], off nt
	global_load_dword v71, v[32:33], off nt
	global_load_dword v72, v[30:31], off nt
	global_load_dword v73, v[36:37], off nt
	global_load_dword v74, v[34:35], off nt
	global_load_dword v75, v[42:43], off nt
	global_load_dword v76, v[40:41], off nt
	global_load_dword v77, v[46:47], off nt
	global_load_dword v78, v[44:45], off nt
	s_add_i32 s5, s5, 16
	s_add_i32 s4, s4, 16
	s_add_i32 s7, s7, -16
	v_mad_u64_u32 v[2:3], s[8:9], v48, s26, v[18:19]
	s_cmp_lg_u32 s7, 0
	v_mad_u64_u32 v[4:5], s[8:9], v0, s26, v[18:19]
	v_mad_u64_u32 v[6:7], s[8:9], v50, s26, v[18:19]
	v_mad_u64_u32 v[8:9], s[8:9], v49, s26, v[18:19]
	v_mad_u64_u32 v[10:11], s[8:9], v52, s26, v[18:19]
	v_mad_u64_u32 v[12:13], s[8:9], v51, s26, v[18:19]
	v_mad_u64_u32 v[26:27], s[8:9], v54, s26, v[18:19]
	v_mad_u64_u32 v[28:29], s[8:9], v53, s26, v[18:19]
	v_mad_u64_u32 v[30:31], s[8:9], v56, s26, v[18:19]
	v_mad_u64_u32 v[32:33], s[8:9], v55, s26, v[18:19]
	v_mad_u64_u32 v[34:35], s[8:9], v58, s26, v[18:19]
	v_mad_u64_u32 v[36:37], s[8:9], v57, s26, v[18:19]
	v_mad_u64_u32 v[40:41], s[8:9], v60, s26, v[18:19]
	v_mad_u64_u32 v[42:43], s[8:9], v59, s26, v[18:19]
	v_mad_u64_u32 v[44:45], s[8:9], v62, s26, v[18:19]
	v_mad_u64_u32 v[46:47], s[8:9], v61, s26, v[18:19]
	s_waitcnt vmcnt(15)
	ds_write_b32 v2, v63
	s_waitcnt vmcnt(14)
	ds_write_b32 v4, v64
	s_waitcnt vmcnt(13)
	ds_write_b32 v6, v65
	s_waitcnt vmcnt(12)
	ds_write_b32 v8, v66
	s_waitcnt vmcnt(11)
	ds_write_b32 v10, v67
	s_waitcnt vmcnt(10)
	ds_write_b32 v12, v68
	s_waitcnt vmcnt(9)
	ds_write_b32 v26, v69
	s_waitcnt vmcnt(8)
	ds_write_b32 v28, v70
	s_waitcnt vmcnt(7)
	ds_write_b32 v30, v71
	s_waitcnt vmcnt(6)
	ds_write_b32 v32, v72
	s_waitcnt vmcnt(5)
	ds_write_b32 v34, v73
	s_waitcnt vmcnt(4)
	ds_write_b32 v36, v74
	s_waitcnt vmcnt(3)
	ds_write_b32 v40, v75
	s_waitcnt vmcnt(2)
	ds_write_b32 v42, v76
	s_waitcnt vmcnt(1)
	ds_write_b32 v44, v77
	s_waitcnt vmcnt(0)
	ds_write_b32 v46, v78
	s_cbranch_scc1 .LBB0_1445
; #define LAS __attribute__((address_space(3)))
; __device__ __forceinline__ v4u pack8(const float (&f)[8]) { v4u w; w.x = cvt_pk_bf16(f[0], f[1]); w.y = cvt_pk_bf16(f[2], f[3]); w.z = cvt_pk_bf16(f[4], f[5]); w.w = cvt_pk_bf16(f[6], f[7]); return w; }
; __device__ __forceinline__ void tr_item(const float* __restrict__ W, int ldw, int k0, int n0, bf16* __restrict__ WT, int ldt, int drow, const float* __restrict__ mu, LAS float* scr, int lane, const float* __restrict__ gs = nullptr) {
;     ...
;     if (mu) {
; #pragma unroll
;         for (int e = 0; e < 8; ++e) mv[e] = mu[k0 + 8 * c + e];
;     } else if (gs) {
; #pragma unroll
;         for (int e = 0; e < 8; ++e) mv[e] = gs[k0 + 8 * c + e];
;     }
; #pragma unroll
;     for (int j = 0; j < 4; ++j) {
;         const int n = (lane >> 3) + 8 * j; const LAS float* s = scr + (8 * c) * 33 + n;
;         float f[8];
; #pragma unroll
;         for (int e = 0; e < 8; ++e) f[e] = s[e * 33];
;         bf16* dp = WT + (size_t)(drow + n) * ldt + k0 + 8 * c;
;         if (mu) {
;             float f1[8], f2[8];
; #pragma unroll
;             for (int e = 0; e < 8; ++e) { f1[e] = f[e] * (1.f - mv[e]); f2[e] = f[e] * mv[e]; }
;             *(v4u*)dp = pack8(f1); *(v4u*)(dp + 1024) = pack8(f2);
	v_readlane_b32 s4, v253, 14
	v_or_b32_e32 v0, s0, v20
	v_readlane_b32 s5, v253, 15
	s_waitcnt lgkmcnt(0)
	s_mov_b32 s1, s95
	v_lshl_add_u64 v[6:7], s[0:1], 1, v[22:23]
	v_lshl_add_u64 v[2:3], v[0:1], 2, s[4:5]
	global_load_dwordx4 v[8:11], v[2:3], off
	s_nop 0
	global_load_dwordx4 v[2:5], v[2:3], off offset:16
	ds_read2_b32 v[12:13], v19 offset0:33 offset1:41
	ds_read2_b32 v[30:31], v19 offset0:66 offset1:74
	ds_read2_b32 v[32:33], v19 offset0:99 offset1:107
	ds_read2_b32 v[34:35], v19 offset0:132 offset1:140
	ds_read2_b32 v[36:37], v19 offset0:165 offset1:173
	ds_read2_b32 v[40:41], v19 offset0:198 offset1:206
	ds_read2_b32 v[42:43], v19 offset0:231 offset1:239
	s_mov_b32 s0, 0xd20000
	ds_read2_b32 v[44:45], v19 offset1:8
	ds_read2_b32 v[46:47], v19 offset0:16 offset1:24
	ds_read2_b32 v[48:49], v19 offset0:49 offset1:57
	ds_read2_b32 v[50:51], v19 offset0:82 offset1:90
	v_add_co_u32_e32 v52, vcc, s0, v6
	s_mov_b32 s0, 0xd28000
	s_nop 0
	v_addc_co_u32_e32 v53, vcc, 0, v7, vcc
	v_add_co_u32_e32 v54, vcc, s0, v6
	s_mov_b32 s0, 0xd30000
	s_nop 0
	v_addc_co_u32_e32 v55, vcc, 0, v7, vcc
	s_waitcnt vmcnt(1) lgkmcnt(3)
	v_mul_f32_e32 v26, v8, v44
	v_mul_f32_e32 v27, v9, v12
	v_sub_f32_e32 v57, 1.0, v10
	v_mul_f32_e32 v28, v10, v30
	v_sub_f32_e32 v58, 1.0, v11
	v_mul_f32_e32 v29, v11, v32
	s_waitcnt vmcnt(0)
	v_mul_f32_e32 v60, v2, v34
	v_sub_f32_e32 v61, 1.0, v3
	v_mul_f32_e32 v62, v3, v36
	v_sub_f32_e32 v0, 1.0, v8
	v_sub_f32_e32 v56, 1.0, v9
	v_sub_f32_e32 v59, 1.0, v2
	v_sub_f32_e32 v63, 1.0, v4
	v_mul_f32_e32 v64, v4, v40
	v_sub_f32_e32 v65, 1.0, v5
	v_mul_f32_e32 v66, v5, v42
	v_mul_f32_e32 v67, v8, v45
	v_mul_f32_e32 v68, v9, v13
	v_mul_f32_e32 v69, v10, v31
	v_mul_f32_e32 v70, v11, v33
	v_mul_f32_e32 v71, v2, v35
	v_mul_f32_e32 v72, v3, v37
	v_mul_f32_e32 v73, v4, v41
	v_mul_f32_e32 v74, v5, v43
	v_mul_f32_e32 v75, v57, v30
	v_mul_f32_e32 v76, v58, v32
	v_mul_f32_e32 v36, v61, v36
	v_cvt_pk_bf16_f32 v26, v26, v27
	v_cvt_pk_bf16_f32 v27, v28, v29
	v_cvt_pk_bf16_f32 v28, v60, v62
	v_cvt_pk_bf16_f32 v29, v64, v66
	v_mul_f32_e32 v60, v57, v31
	v_mul_f32_e32 v62, v58, v33
	v_cvt_pk_bf16_f32 v30, v67, v68
	v_cvt_pk_bf16_f32 v31, v69, v70
	v_cvt_pk_bf16_f32 v32, v71, v72
	v_cvt_pk_bf16_f32 v33, v73, v74
	v_mul_f32_e32 v44, v0, v44
	v_mul_f32_e32 v12, v56, v12
	v_mul_f32_e32 v77, v59, v34
	v_mul_f32_e32 v40, v63, v40
	v_mul_f32_e32 v42, v65, v42
	v_mul_f32_e32 v45, v0, v45
	v_mul_f32_e32 v13, v56, v13
	v_mul_f32_e32 v64, v59, v35
	v_mul_f32_e32 v66, v61, v37
	v_mul_f32_e32 v41, v63, v41
	v_mul_f32_e32 v43, v65, v43
	v_cvt_pk_bf16_f32 v34, v44, v12
	v_cvt_pk_bf16_f32 v35, v75, v76
	v_cvt_pk_bf16_f32 v36, v77, v36
	v_cvt_pk_bf16_f32 v37, v40, v42
	global_store_dwordx4 v[52:53], v[26:29], off offset:2048 nt
	s_waitcnt lgkmcnt(2)
	v_mul_f32_e32 v42, v8, v46
	s_waitcnt lgkmcnt(0)
	v_mul_f32_e32 v44, v10, v50
	v_cvt_pk_bf16_f32 v26, v45, v13
	v_cvt_pk_bf16_f32 v27, v60, v62
	v_cvt_pk_bf16_f32 v28, v64, v66
	v_cvt_pk_bf16_f32 v29, v41, v43
	global_store_dwordx4 v[54:55], v[30:33], off offset:2048 nt
	global_store_dwordx4 v[52:53], v[34:37], off nt
	global_store_dwordx4 v[54:55], v[26:29], off nt
	ds_read2_b32 v[12:13], v19 offset0:115 offset1:123
	ds_read2_b32 v[30:31], v19 offset0:148 offset1:156
	ds_read2_b32 v[32:33], v19 offset0:181 offset1:189
	ds_read2_b32 v[34:35], v19 offset0:214 offset1:222
	ds_read2_b32 v[36:37], v19 offset0:247 offset1:255
	v_mul_f32_e32 v26, v0, v46
	v_mul_f32_e32 v27, v56, v48
	v_mul_f32_e32 v28, v57, v50
	s_waitcnt lgkmcnt(3)
	v_mul_f32_e32 v40, v59, v30
	v_mul_f32_e32 v29, v58, v12
	s_waitcnt lgkmcnt(2)
	v_mul_f32_e32 v41, v61, v32
	v_cvt_pk_bf16_f32 v26, v26, v27
	v_cvt_pk_bf16_f32 v27, v28, v29
	v_cvt_pk_bf16_f32 v28, v40, v41
	v_add_co_u32_e32 v40, vcc, s0, v6
	s_waitcnt lgkmcnt(1)
	v_mul_f32_e32 v45, v63, v34
	s_waitcnt lgkmcnt(0)
	v_mul_f32_e32 v46, v65, v36
	v_cvt_pk_bf16_f32 v29, v45, v46
	v_addc_co_u32_e32 v41, vcc, 0, v7, vcc
	v_mul_f32_e32 v43, v9, v48
	v_mul_f32_e32 v12, v11, v12
	v_mul_f32_e32 v30, v2, v30
	v_mul_f32_e32 v32, v3, v32
	v_mul_f32_e32 v34, v4, v34
	v_mul_f32_e32 v36, v5, v36
	global_store_dwordx4 v[40:41], v[26:29], off nt
	v_add_co_u32_e32 v6, vcc, 0xd38000, v6
	s_nop 0
	v_cvt_pk_bf16_f32 v26, v42, v43
	v_cvt_pk_bf16_f32 v27, v44, v12
	v_cvt_pk_bf16_f32 v28, v30, v32
	v_cvt_pk_bf16_f32 v29, v34, v36
	global_store_dwordx4 v[40:41], v[26:29], off offset:2048 nt
	v_mul_f32_e32 v0, v0, v47
	v_mul_f32_e32 v12, v56, v49
	v_mul_f32_e32 v26, v57, v51
	v_mul_f32_e32 v27, v58, v13
	v_mul_f32_e32 v11, v11, v13
	v_mul_f32_e32 v13, v59, v31
	v_mul_f32_e32 v28, v2, v31
	v_mul_f32_e32 v29, v61, v33
	v_mul_f32_e32 v30, v3, v33
	v_mul_f32_e32 v31, v63, v35
	v_mul_f32_e32 v32, v4, v35
	v_mul_f32_e32 v33, v65, v37
	v_mul_f32_e32 v34, v5, v37
	v_cvt_pk_bf16_f32 v2, v0, v12
	v_cvt_pk_bf16_f32 v3, v26, v27
	v_cvt_pk_bf16_f32 v4, v13, v29
	v_cvt_pk_bf16_f32 v5, v31, v33
	v_addc_co_u32_e32 v7, vcc, 0, v7, vcc
	v_mul_f32_e32 v8, v8, v47
	v_mul_f32_e32 v9, v9, v49
	v_mul_f32_e32 v10, v10, v51
	global_store_dwordx4 v[6:7], v[2:5], off nt
	s_nop 1
	v_cvt_pk_bf16_f32 v2, v8, v9
	v_cvt_pk_bf16_f32 v3, v10, v11
	v_cvt_pk_bf16_f32 v4, v28, v30
	v_cvt_pk_bf16_f32 v5, v32, v34
	global_store_dwordx4 v[6:7], v[2:5], off offset:2048 nt
	s_waitcnt lgkmcnt(0)

; __device__ __forceinline__ void tr_item(const float* __restrict__ W, int ldw, int k0, int n0, bf16* __restrict__ WT, int ldt, int drow, const float* __restrict__ mu, LAS float* scr, int lane, const float* __restrict__ gs = nullptr) {
; #pragma unroll 8
;     for (int i = 0; i < 32; ++i) { const int kk = 2 * i + (lane >> 5); scr[kk * 33 + (lane & 31)] = W[(size_t)(k0 + kk) * ldw + n0 + (lane & 31)]; }
;     asm volatile("s_waitcnt lgkmcnt(0)" ::: "memory");
.LBB0_1450:
	s_lshl_b32 s10, s8, 1
	s_lshl_b32 s11, s5, 1
	v_or_b32_e32 v0, s10, v15
	v_or_b32_e32 v50, s11, v14
	s_add_i32 s12, s10, 4
	s_add_i32 s13, s11, 4
	s_add_i32 s14, s10, 8
	s_add_i32 s15, s11, 8
	s_add_i32 s16, s10, 12
	s_add_i32 s17, s11, 12
	s_add_i32 s18, s10, 16
	s_add_i32 s19, s11, 16
	s_add_i32 s20, s10, 20
	s_add_i32 s21, s11, 20
	s_add_i32 s22, s10, 24
	s_add_i32 s23, s11, 24
	s_add_i32 s10, s10, 28
	s_add_i32 s11, s11, 28
	v_add_u32_e32 v4, s4, v50
	v_or_b32_e32 v51, s12, v15
	v_or_b32_e32 v52, s13, v14
	v_or_b32_e32 v53, s14, v15
	v_or_b32_e32 v54, s15, v14
	v_or_b32_e32 v55, s16, v15
	v_or_b32_e32 v56, s17, v14
	v_or_b32_e32 v57, s18, v15
	v_or_b32_e32 v58, s19, v14
	v_or_b32_e32 v59, s20, v15
	v_or_b32_e32 v60, s21, v14
	v_or_b32_e32 v61, s22, v15
	v_or_b32_e32 v62, s23, v14
	v_or_b32_e32 v63, s10, v15
	v_or_b32_e32 v64, s11, v14
	v_add_u32_e32 v6, s7, v0
	v_mad_u64_u32 v[4:5], s[10:11], v4, s25, v[2:3]
	v_add_u32_e32 v10, s7, v51
	v_add_u32_e32 v8, s4, v52
	v_add_u32_e32 v26, s7, v53
	s_waitcnt lgkmcnt(0)
	v_add_u32_e32 v12, s4, v54
	v_add_u32_e32 v30, s7, v55
	v_add_u32_e32 v28, s4, v56
	v_add_u32_e32 v34, s7, v57
	v_add_u32_e32 v32, s4, v58
	v_add_u32_e32 v40, s7, v59
	v_add_u32_e32 v36, s4, v60
	v_add_u32_e32 v44, s7, v61
	v_add_u32_e32 v42, s4, v62
	v_add_u32_e32 v48, s7, v63
	v_add_u32_e32 v46, s4, v64
	v_mad_u64_u32 v[6:7], s[10:11], v6, s25, v[2:3]
	v_mad_u64_u32 v[8:9], s[10:11], v8, s25, v[2:3]
	v_mad_u64_u32 v[10:11], s[10:11], v10, s25, v[2:3]
	v_mad_u64_u32 v[12:13], s[10:11], v12, s25, v[2:3]
	v_mad_u64_u32 v[26:27], s[10:11], v26, s25, v[2:3]
	v_mad_u64_u32 v[28:29], s[10:11], v28, s25, v[2:3]
	v_mad_u64_u32 v[30:31], s[10:11], v30, s25, v[2:3]
	v_mad_u64_u32 v[32:33], s[10:11], v32, s25, v[2:3]
	v_mad_u64_u32 v[34:35], s[10:11], v34, s25, v[2:3]
	v_mad_u64_u32 v[36:37], s[10:11], v36, s25, v[2:3]
	v_mad_u64_u32 v[40:41], s[10:11], v40, s25, v[2:3]
	v_mad_u64_u32 v[42:43], s[10:11], v42, s25, v[2:3]
	v_mad_u64_u32 v[44:45], s[10:11], v44, s25, v[2:3]
	v_mad_u64_u32 v[46:47], s[10:11], v46, s25, v[2:3]
	v_mad_u64_u32 v[48:49], s[10:11], v48, s25, v[2:3]
	global_load_dword v65, v[4:5], off nt
	global_load_dword v66, v[6:7], off nt
	global_load_dword v67, v[8:9], off nt
	global_load_dword v68, v[10:11], off nt
	global_load_dword v69, v[12:13], off nt
	global_load_dword v70, v[26:27], off nt
	global_load_dword v71, v[28:29], off nt
	global_load_dword v72, v[30:31], off nt
	global_load_dword v73, v[32:33], off nt
	global_load_dword v74, v[34:35], off nt
	global_load_dword v75, v[36:37], off nt
	global_load_dword v76, v[40:41], off nt
	global_load_dword v77, v[42:43], off nt
	global_load_dword v78, v[44:45], off nt
	global_load_dword v79, v[46:47], off nt
	global_load_dword v80, v[48:49], off nt
	s_add_i32 s5, s5, 16
	s_add_i32 s8, s8, 16
	s_add_i32 s9, s9, -16
	v_mad_u64_u32 v[4:5], s[10:11], v50, s26, v[18:19]
	s_cmp_lg_u32 s9, 0
	v_mad_u64_u32 v[6:7], s[10:11], v0, s26, v[18:19]
	v_mad_u64_u32 v[8:9], s[10:11], v52, s26, v[18:19]
	v_mad_u64_u32 v[10:11], s[10:11], v51, s26, v[18:19]
	v_mad_u64_u32 v[12:13], s[10:11], v54, s26, v[18:19]
	v_mad_u64_u32 v[26:27], s[10:11], v53, s26, v[18:19]
	v_mad_u64_u32 v[28:29], s[10:11], v56, s26, v[18:19]
	v_mad_u64_u32 v[30:31], s[10:11], v55, s26, v[18:19]
	v_mad_u64_u32 v[32:33], s[10:11], v58, s26, v[18:19]
	v_mad_u64_u32 v[34:35], s[10:11], v57, s26, v[18:19]
	v_mad_u64_u32 v[36:37], s[10:11], v60, s26, v[18:19]
	v_mad_u64_u32 v[40:41], s[10:11], v59, s26, v[18:19]
	v_mad_u64_u32 v[42:43], s[10:11], v62, s26, v[18:19]
	v_mad_u64_u32 v[44:45], s[10:11], v61, s26, v[18:19]
	v_mad_u64_u32 v[46:47], s[10:11], v64, s26, v[18:19]
	v_mad_u64_u32 v[48:49], s[10:11], v63, s26, v[18:19]
	s_waitcnt vmcnt(15)
	ds_write_b32 v4, v65
	s_waitcnt vmcnt(14)
	ds_write_b32 v6, v66
	s_waitcnt vmcnt(13)
	ds_write_b32 v8, v67
	s_waitcnt vmcnt(12)
	ds_write_b32 v10, v68
	s_waitcnt vmcnt(11)
	ds_write_b32 v12, v69
	s_waitcnt vmcnt(10)
	ds_write_b32 v26, v70
	s_waitcnt vmcnt(9)
	ds_write_b32 v28, v71
	s_waitcnt vmcnt(8)
	ds_write_b32 v30, v72
	s_waitcnt vmcnt(7)
	ds_write_b32 v32, v73
	s_waitcnt vmcnt(6)
	ds_write_b32 v34, v74
	s_waitcnt vmcnt(5)
	ds_write_b32 v36, v75
	s_waitcnt vmcnt(4)
	ds_write_b32 v40, v76
	s_waitcnt vmcnt(3)
	ds_write_b32 v42, v77
	s_waitcnt vmcnt(2)
	ds_write_b32 v44, v78
	s_waitcnt vmcnt(1)
	ds_write_b32 v46, v79
	s_waitcnt vmcnt(0)
	ds_write_b32 v48, v80
	s_cbranch_scc1 .LBB0_1450
; #define LAS __attribute__((address_space(3)))
; __device__ __forceinline__ v4u pack8(const float (&f)[8]) { v4u w; w.x = cvt_pk_bf16(f[0], f[1]); w.y = cvt_pk_bf16(f[2], f[3]); w.z = cvt_pk_bf16(f[4], f[5]); w.w = cvt_pk_bf16(f[6], f[7]); return w; }
; __device__ __forceinline__ void tr_item(const float* __restrict__ W, int ldw, int k0, int n0, bf16* __restrict__ WT, int ldt, int drow, const float* __restrict__ mu, LAS float* scr, int lane, const float* __restrict__ gs = nullptr) {
;     ...
;     if (mu) {
; #pragma unroll
;         for (int e = 0; e < 8; ++e) mv[e] = mu[k0 + 8 * c + e];
;     } else if (gs) {
; #pragma unroll
;         for (int e = 0; e < 8; ++e) mv[e] = gs[k0 + 8 * c + e];
;     }
; #pragma unroll
;     for (int j = 0; j < 4; ++j) {
;         const int n = (lane >> 3) + 8 * j; const LAS float* s = scr + (8 * c) * 33 + n;
;         float f[8];
; #pragma unroll
;         for (int e = 0; e < 8; ++e) f[e] = s[e * 33];
;         bf16* dp = WT + (size_t)(drow + n) * ldt + k0 + 8 * c;
;         if (mu) {
;             float f1[8], f2[8];
; #pragma unroll
;             for (int e = 0; e < 8; ++e) { f1[e] = f[e] * (1.f - mv[e]); f2[e] = f[e] * mv[e]; }
;             *(v4u*)dp = pack8(f1); *(v4u*)(dp + 1024) = pack8(f2);
	s_and_b64 s[8:9], s[0:1], exec
	s_cselect_b32 s5, 0xe00000, 0
	s_add_u32 s5, s36, s5
	s_addc_u32 s7, s37, 0
	s_and_b64 s[0:1], s[0:1], exec
	s_mov_b32 s0, 0xb000
	s_cselect_b32 s1, s0, 0x5000
	s_add_i32 s0, s94, 0xc80
	s_add_u32 s8, s50, s1
	s_addc_u32 s9, s51, 0
	v_or_b32_e32 v0, s4, v20
	s_waitcnt lgkmcnt(0)
	v_lshl_add_u64 v[6:7], v[0:1], 2, s[8:9]
	global_load_dwordx4 v[2:5], v[6:7], off
	s_nop 0
	global_load_dwordx4 v[6:9], v[6:7], off offset:16
	ds_read2_b32 v[26:27], v19 offset0:33 offset1:41
	ds_read2_b32 v[28:29], v19 offset0:66 offset1:74
	ds_read2_b32 v[30:31], v19 offset0:99 offset1:107
	ds_read2_b32 v[32:33], v19 offset0:132 offset1:140
	ds_read2_b32 v[34:35], v19 offset0:165 offset1:173
	ds_read2_b32 v[36:37], v19 offset0:198 offset1:206
	ds_read2_b32 v[40:41], v19 offset0:231 offset1:239
	ds_read2_b32 v[42:43], v19 offset1:8
	s_lshl_b32 s1, s4, 1
	s_add_u32 s4, s5, s1
	v_or_b32_e32 v10, s0, v17
	v_lshlrev_b32_e32 v0, 1, v20
	s_addc_u32 s5, s7, 0
	v_or_b32_e32 v11, s0, v21
	v_lshl_add_u64 v[44:45], s[4:5], 0, v[0:1]
	v_lshlrev_b32_e32 v0, 12, v10
	v_lshl_add_u64 v[46:47], v[44:45], 0, v[0:1]
	v_lshlrev_b32_e32 v0, 12, v11
	v_lshl_add_u64 v[48:49], v[44:45], 0, v[0:1]
	s_waitcnt vmcnt(1)
	v_sub_f32_e32 v50, 1.0, v2
	s_waitcnt lgkmcnt(0)
	v_mul_f32_e32 v0, v2, v42
	v_sub_f32_e32 v51, 1.0, v3
	v_mul_f32_e32 v10, v3, v26
	v_sub_f32_e32 v52, 1.0, v4
	v_mul_f32_e32 v11, v4, v28
	v_mul_f32_e32 v12, v5, v30
	s_waitcnt vmcnt(0)
	v_sub_f32_e32 v54, 1.0, v6
	v_mul_f32_e32 v13, v6, v32
	v_mul_f32_e32 v56, v7, v34
	v_sub_f32_e32 v53, 1.0, v5
	v_sub_f32_e32 v55, 1.0, v7
	v_sub_f32_e32 v57, 1.0, v8
	v_mul_f32_e32 v58, v8, v36
	v_sub_f32_e32 v59, 1.0, v9
	v_mul_f32_e32 v60, v9, v40
	v_mul_f32_e32 v61, v2, v43
	v_mul_f32_e32 v62, v3, v27
	v_mul_f32_e32 v63, v4, v29
	v_mul_f32_e32 v64, v5, v31
	v_mul_f32_e32 v65, v6, v33
	v_mul_f32_e32 v66, v7, v35
	v_mul_f32_e32 v67, v8, v37
	v_mul_f32_e32 v68, v9, v41
	v_mul_f32_e32 v69, v51, v26
	v_mul_f32_e32 v70, v52, v28
	v_mul_f32_e32 v32, v54, v32
	v_cvt_pk_bf16_f32 v10, v0, v10
	v_cvt_pk_bf16_f32 v11, v11, v12
	v_cvt_pk_bf16_f32 v12, v13, v56
	v_cvt_pk_bf16_f32 v13, v58, v60
	v_mul_f32_e32 v0, v50, v43
	v_mul_f32_e32 v43, v51, v27
	v_mul_f32_e32 v56, v52, v29
	v_cvt_pk_bf16_f32 v26, v61, v62
	v_cvt_pk_bf16_f32 v27, v63, v64
	v_cvt_pk_bf16_f32 v28, v65, v66
	v_cvt_pk_bf16_f32 v29, v67, v68
	v_mul_f32_e32 v42, v50, v42
	v_mul_f32_e32 v71, v53, v30
	v_mul_f32_e32 v34, v55, v34
	v_mul_f32_e32 v36, v57, v36
	v_mul_f32_e32 v40, v59, v40
	v_mul_f32_e32 v58, v53, v31
	v_mul_f32_e32 v60, v54, v33
	v_mul_f32_e32 v35, v55, v35
	v_mul_f32_e32 v37, v57, v37
	v_mul_f32_e32 v41, v59, v41
	v_cvt_pk_bf16_f32 v30, v42, v69
	v_cvt_pk_bf16_f32 v31, v70, v71
	v_cvt_pk_bf16_f32 v32, v32, v34
	v_cvt_pk_bf16_f32 v33, v36, v40
	global_store_dwordx4 v[46:47], v[10:13], off offset:2048 nt
	s_nop 1
	v_cvt_pk_bf16_f32 v10, v0, v43
	v_cvt_pk_bf16_f32 v11, v56, v58
	v_cvt_pk_bf16_f32 v12, v60, v35
	v_cvt_pk_bf16_f32 v13, v37, v41
	global_store_dwordx4 v[48:49], v[26:29], off offset:2048 nt
	global_store_dwordx4 v[46:47], v[30:33], off nt
	global_store_dwordx4 v[48:49], v[10:13], off nt
	ds_read2_b32 v[26:27], v19 offset0:16 offset1:24
	ds_read2_b32 v[28:29], v19 offset0:49 offset1:57
	ds_read2_b32 v[30:31], v19 offset0:82 offset1:90
	ds_read2_b32 v[32:33], v19 offset0:115 offset1:123
	ds_read2_b32 v[34:35], v19 offset0:148 offset1:156
	ds_read2_b32 v[36:37], v19 offset0:181 offset1:189
	ds_read2_b32 v[40:41], v19 offset0:214 offset1:222
	ds_read2_b32 v[42:43], v19 offset0:247 offset1:255
	v_or_b32_e32 v0, s0, v38
	v_lshlrev_b32_e32 v0, 12, v0
	v_lshl_add_u64 v[46:47], v[44:45], 0, v[0:1]
	s_waitcnt lgkmcnt(7)
	v_mul_f32_e32 v0, v50, v26
	s_waitcnt lgkmcnt(6)
	v_mul_f32_e32 v10, v51, v28
	s_waitcnt lgkmcnt(5)
	v_mul_f32_e32 v11, v52, v30
	s_waitcnt lgkmcnt(4)
	v_mul_f32_e32 v12, v53, v32
	s_waitcnt lgkmcnt(3)
	v_mul_f32_e32 v13, v54, v34
	s_waitcnt lgkmcnt(2)
	v_mul_f32_e32 v48, v55, v36
	s_waitcnt lgkmcnt(1)
	v_mul_f32_e32 v49, v57, v40
	s_waitcnt lgkmcnt(0)
	v_mul_f32_e32 v56, v59, v42
	v_cvt_pk_bf16_f32 v10, v0, v10
	v_cvt_pk_bf16_f32 v11, v11, v12
	v_cvt_pk_bf16_f32 v12, v13, v48
	v_cvt_pk_bf16_f32 v13, v49, v56
	v_or_b32_e32 v0, s0, v39
	v_mul_f32_e32 v26, v2, v26
	v_mul_f32_e32 v28, v3, v28
	v_mul_f32_e32 v30, v4, v30
	v_mul_f32_e32 v32, v5, v32
	v_mul_f32_e32 v34, v6, v34
	v_mul_f32_e32 v36, v7, v36
	v_mul_f32_e32 v40, v8, v40
	v_mul_f32_e32 v42, v9, v42
	global_store_dwordx4 v[46:47], v[10:13], off nt
	v_lshlrev_b32_e32 v0, 12, v0
	v_mul_f32_e32 v6, v6, v35
	v_cvt_pk_bf16_f32 v10, v26, v28
	v_cvt_pk_bf16_f32 v11, v30, v32
	v_cvt_pk_bf16_f32 v12, v34, v36
	v_cvt_pk_bf16_f32 v13, v40, v42
	global_store_dwordx4 v[46:47], v[10:13], off offset:2048 nt
	v_mul_f32_e32 v26, v4, v31
	v_mul_f32_e32 v4, v53, v33
	v_lshl_add_u64 v[10:11], v[44:45], 0, v[0:1]
	v_mul_f32_e32 v0, v50, v27
	v_mul_f32_e32 v12, v2, v27
	v_mul_f32_e32 v2, v51, v29
	v_mul_f32_e32 v13, v3, v29
	v_mul_f32_e32 v3, v52, v31
	v_mul_f32_e32 v27, v5, v33
	v_mul_f32_e32 v5, v54, v35
	v_mul_f32_e32 v28, v55, v37
	v_mul_f32_e32 v29, v57, v41
	v_mul_f32_e32 v30, v59, v43
	v_cvt_pk_bf16_f32 v2, v0, v2
	v_cvt_pk_bf16_f32 v3, v3, v4
	v_cvt_pk_bf16_f32 v4, v5, v28
	v_cvt_pk_bf16_f32 v5, v29, v30
	v_mul_f32_e32 v7, v7, v37
	v_mul_f32_e32 v8, v8, v41
	v_mul_f32_e32 v9, v9, v43
	global_store_dwordx4 v[10:11], v[2:5], off nt
	s_nop 1
	v_cvt_pk_bf16_f32 v2, v12, v13
	v_cvt_pk_bf16_f32 v3, v26, v27
	v_cvt_pk_bf16_f32 v4, v6, v7
	v_cvt_pk_bf16_f32 v5, v8, v9
	global_store_dwordx4 v[10:11], v[2:5], off offset:2048 nt
	s_waitcnt lgkmcnt(0)

; __device__ __forceinline__ void tr_item(const float* __restrict__ W, int ldw, int k0, int n0, bf16* __restrict__ WT, int ldt, int drow, const float* __restrict__ mu, LAS float* scr, int lane, const float* __restrict__ gs = nullptr) {
; #pragma unroll 8
;     for (int i = 0; i < 32; ++i) { const int kk = 2 * i + (lane >> 5); scr[kk * 33 + (lane & 31)] = W[(size_t)(k0 + kk) * ldw + n0 + (lane & 31)]; }
.LBB0_1455:
	s_lshl_b32 s9, s7, 1
	s_lshl_b32 s10, s8, 1
	v_or_b32_e32 v41, s10, v14
	s_add_i32 s11, s9, 4
	s_add_i32 s12, s10, 4
	s_add_i32 s14, s10, 8
	v_add_u32_e32 v0, s0, v41
	v_or_b32_e32 v42, s11, v15
	v_or_b32_e32 v43, s12, v14
	v_mov_b32_e32 v7, v1
	v_or_b32_e32 v40, s9, v15
	s_add_i32 s16, s10, 12
	v_or_b32_e32 v45, s14, v14
	s_waitcnt lgkmcnt(3)
	v_lshlrev_b64 v[32:33], 8, v[0:1]
	v_add_u32_e32 v6, s5, v42
	v_add_u32_e32 v0, s0, v43
	v_mov_b32_e32 v5, v1
	s_add_i32 s13, s9, 8
	s_add_i32 s15, s9, 12
	s_add_i32 s18, s10, 16
	v_add_u32_e32 v4, s5, v40
	v_or_b32_e32 v47, s16, v14
	v_lshlrev_b64 v[6:7], 8, v[6:7]
	v_lshlrev_b64 v[34:35], 8, v[0:1]
	v_add_u32_e32 v0, s0, v45
	s_add_i32 s20, s10, 20
	v_or_b32_e32 v44, s13, v15
	v_or_b32_e32 v46, s15, v15
	v_or_b32_e32 v49, s18, v14
	v_lshlrev_b64 v[4:5], 8, v[4:5]
	v_lshl_add_u64 v[32:33], v[2:3], 0, v[32:33]
	v_lshl_add_u64 v[6:7], v[2:3], 0, v[6:7]
	v_lshlrev_b64 v[36:37], 8, v[0:1]
	v_add_u32_e32 v0, s0, v47
	v_mov_b32_e32 v9, v1
	v_mov_b32_e32 v11, v1
	s_add_i32 s17, s9, 16
	s_add_i32 s19, s9, 20
	s_add_i32 s22, s10, 24
	v_or_b32_e32 v51, s20, v14
	v_add_u32_e32 v8, s5, v44
	v_add_u32_e32 v10, s5, v46
	v_lshl_add_u64 v[4:5], v[2:3], 0, v[4:5]
	v_lshl_add_u64 v[34:35], v[2:3], 0, v[34:35]
	global_load_dword v56, v[32:33], off nt
	global_load_dword v57, v[4:5], off nt
	global_load_dword v58, v[34:35], off nt
	global_load_dword v59, v[6:7], off nt
	v_lshlrev_b64 v[6:7], 8, v[0:1]
	v_add_u32_e32 v0, s0, v49
	s_add_i32 s21, s9, 24
	s_add_i32 s9, s9, 28
	s_add_i32 s10, s10, 28
	v_or_b32_e32 v48, s17, v15
	v_or_b32_e32 v50, s19, v15
	v_or_b32_e32 v53, s22, v14
	v_lshlrev_b64 v[8:9], 8, v[8:9]
	v_lshlrev_b64 v[10:11], 8, v[10:11]
	v_lshl_add_u64 v[4:5], v[2:3], 0, v[36:37]
	v_lshl_add_u64 v[6:7], v[2:3], 0, v[6:7]
	v_lshlrev_b64 v[32:33], 8, v[0:1]
	v_add_u32_e32 v0, s0, v51
	s_waitcnt lgkmcnt(0)
	v_mov_b32_e32 v13, v1
	v_mov_b32_e32 v27, v1
	v_or_b32_e32 v52, s21, v15
	v_or_b32_e32 v54, s9, v15
	v_or_b32_e32 v55, s10, v14
	v_add_u32_e32 v12, s5, v48
	v_add_u32_e32 v26, s5, v50
	v_lshl_add_u64 v[8:9], v[2:3], 0, v[8:9]
	v_lshl_add_u64 v[10:11], v[2:3], 0, v[10:11]
	global_load_dword v60, v[4:5], off nt
	global_load_dword v61, v[8:9], off nt
	global_load_dword v62, v[6:7], off nt
	global_load_dword v63, v[10:11], off nt
	v_lshlrev_b64 v[6:7], 8, v[0:1]
	v_add_u32_e32 v0, s0, v53
	v_mov_b32_e32 v29, v1
	v_mov_b32_e32 v31, v1
	v_add_u32_e32 v28, s5, v52
	v_add_u32_e32 v30, s5, v54
	v_lshlrev_b64 v[12:13], 8, v[12:13]
	v_lshlrev_b64 v[26:27], 8, v[26:27]
	v_lshl_add_u64 v[4:5], v[2:3], 0, v[32:33]
	v_lshl_add_u64 v[6:7], v[2:3], 0, v[6:7]
	v_lshlrev_b64 v[8:9], 8, v[0:1]
	v_add_u32_e32 v0, s0, v55
	v_lshlrev_b64 v[28:29], 8, v[28:29]
	v_lshlrev_b64 v[30:31], 8, v[30:31]
	v_lshl_add_u64 v[12:13], v[2:3], 0, v[12:13]
	v_lshl_add_u64 v[26:27], v[2:3], 0, v[26:27]
	global_load_dword v64, v[4:5], off nt
	global_load_dword v65, v[12:13], off nt
	global_load_dword v66, v[6:7], off nt
	global_load_dword v67, v[26:27], off nt
	v_lshl_add_u64 v[4:5], v[2:3], 0, v[8:9]
	v_lshlrev_b64 v[6:7], 8, v[0:1]
	v_lshl_add_u64 v[28:29], v[2:3], 0, v[28:29]
	v_lshl_add_u64 v[30:31], v[2:3], 0, v[30:31]
	v_lshl_add_u64 v[6:7], v[2:3], 0, v[6:7]
	global_load_dword v0, v[4:5], off nt
	global_load_dword v68, v[28:29], off nt
	global_load_dword v69, v[6:7], off nt
	global_load_dword v70, v[30:31], off nt
	s_add_i32 s8, s8, 16
	s_add_i32 s7, s7, 16
	s_add_i32 s4, s4, -16
	v_mad_u64_u32 v[4:5], s[10:11], v41, s26, v[18:19]
	s_cmp_lg_u32 s4, 0
	v_mad_u64_u32 v[6:7], s[10:11], v40, s26, v[18:19]
	v_mad_u64_u32 v[8:9], s[10:11], v43, s26, v[18:19]
	v_mad_u64_u32 v[10:11], s[10:11], v42, s26, v[18:19]
	v_mad_u64_u32 v[12:13], s[10:11], v45, s26, v[18:19]
	v_mad_u64_u32 v[26:27], s[10:11], v44, s26, v[18:19]
	v_mad_u64_u32 v[28:29], s[10:11], v47, s26, v[18:19]
	v_mad_u64_u32 v[30:31], s[10:11], v46, s26, v[18:19]
	v_mad_u64_u32 v[32:33], s[10:11], v49, s26, v[18:19]
	v_mad_u64_u32 v[34:35], s[10:11], v48, s26, v[18:19]
	v_mad_u64_u32 v[36:37], s[10:11], v51, s26, v[18:19]
	v_mad_u64_u32 v[40:41], s[10:11], v50, s26, v[18:19]
	v_mad_u64_u32 v[42:43], s[10:11], v53, s26, v[18:19]
	v_mad_u64_u32 v[44:45], s[10:11], v52, s26, v[18:19]
	v_mad_u64_u32 v[46:47], s[10:11], v55, s26, v[18:19]
	v_mad_u64_u32 v[48:49], s[10:11], v54, s26, v[18:19]
	s_waitcnt vmcnt(15)
	ds_write_b32 v4, v56
	s_waitcnt vmcnt(14)
	ds_write_b32 v6, v57
	s_waitcnt vmcnt(13)
	ds_write_b32 v8, v58
	s_waitcnt vmcnt(12)
	ds_write_b32 v10, v59
	s_waitcnt vmcnt(11)
	ds_write_b32 v12, v60
	s_waitcnt vmcnt(10)
	ds_write_b32 v26, v61
	s_waitcnt vmcnt(9)
	ds_write_b32 v28, v62
	s_waitcnt vmcnt(8)
	ds_write_b32 v30, v63
	s_waitcnt vmcnt(7)
	ds_write_b32 v32, v64
	s_waitcnt vmcnt(6)
	ds_write_b32 v34, v65
	s_waitcnt vmcnt(5)
	ds_write_b32 v36, v66
	s_waitcnt vmcnt(4)
	ds_write_b32 v40, v67
	s_waitcnt vmcnt(3)
	ds_write_b32 v42, v0
	s_waitcnt vmcnt(2)
	ds_write_b32 v44, v68
	s_waitcnt vmcnt(1)
	ds_write_b32 v46, v69
	s_waitcnt vmcnt(0)
	ds_write_b32 v48, v70
	s_cbranch_scc1 .LBB0_1455
; #define LAS __attribute__((address_space(3)))
; __device__ __forceinline__ v4u pack8(const float (&f)[8]) { v4u w; w.x = cvt_pk_bf16(f[0], f[1]); w.y = cvt_pk_bf16(f[2], f[3]); w.z = cvt_pk_bf16(f[4], f[5]); w.w = cvt_pk_bf16(f[6], f[7]); return w; }
; __device__ __forceinline__ void tr_item(const float* __restrict__ W, int ldw, int k0, int n0, bf16* __restrict__ WT, int ldt, int drow, const float* __restrict__ mu, LAS float* scr, int lane, const float* __restrict__ gs = nullptr) {
;     ...
;     if (mu) {
; #pragma unroll
;         for (int e = 0; e < 8; ++e) mv[e] = mu[k0 + 8 * c + e];
;     } else if (gs) {
; #pragma unroll
;         for (int e = 0; e < 8; ++e) mv[e] = gs[k0 + 8 * c + e];
;     }
; #pragma unroll
;     for (int j = 0; j < 4; ++j) {
;         const int n = (lane >> 3) + 8 * j; const LAS float* s = scr + (8 * c) * 33 + n;
;         float f[8];
; #pragma unroll
;         for (int e = 0; e < 8; ++e) f[e] = s[e * 33];
;         bf16* dp = WT + (size_t)(drow + n) * ldt + k0 + 8 * c;
;         if (mu) {
;             float f1[8], f2[8];
; #pragma unroll
;             for (int e = 0; e < 8; ++e) { f1[e] = f[e] * (1.f - mv[e]); f2[e] = f[e] * mv[e]; }
;             *(v4u*)dp = pack8(f1); *(v4u*)(dp + 1024) = pack8(f2);
	s_mul_i32 s7, s94, 6
	s_mul_hi_u32 s4, s94, 0xe00000
	s_mul_i32 s5, s94, 0xe00000
	s_add_i32 s94, s7, 4
	s_add_u32 s7, s36, s5
	s_addc_u32 s8, s37, s4
	s_lshl_b64 s[4:5], s[94:95], 12
	s_or_b32 s1, s1, 0xc40
	s_add_u32 s4, s50, s4
	v_or_b32_e32 v0, s0, v20
	s_addc_u32 s5, s51, s5
	s_waitcnt lgkmcnt(0)
	v_lshlrev_b32_e32 v0, 2, v0
	global_load_dwordx4 v[2:5], v0, s[4:5]
	global_load_dwordx4 v[6:9], v0, s[4:5] offset:16
	ds_read2_b32 v[26:27], v19 offset0:33 offset1:41
	ds_read2_b32 v[28:29], v19 offset0:66 offset1:74
	ds_read2_b32 v[30:31], v19 offset0:99 offset1:107
	ds_read2_b32 v[32:33], v19 offset0:132 offset1:140
	ds_read2_b32 v[34:35], v19 offset0:165 offset1:173
	ds_read2_b32 v[36:37], v19 offset0:198 offset1:206
	ds_read2_b32 v[40:41], v19 offset0:231 offset1:239
	ds_read2_b32 v[42:43], v19 offset1:8
	s_lshl_b32 s0, s0, 1
	s_add_u32 s4, s7, s0
	v_lshlrev_b32_e32 v0, 1, v20
	v_or_b32_e32 v10, s1, v17
	s_addc_u32 s5, s8, 0
	v_or_b32_e32 v11, s1, v21
	v_lshl_add_u64 v[44:45], s[4:5], 0, v[0:1]
	v_lshlrev_b32_e32 v0, 12, v10
	v_lshl_add_u64 v[46:47], v[44:45], 0, v[0:1]
	v_lshlrev_b32_e32 v0, 12, v11
	v_lshl_add_u64 v[48:49], v[44:45], 0, v[0:1]
	s_waitcnt vmcnt(1)
	v_sub_f32_e32 v53, 1.0, v5
	v_sub_f32_e32 v50, 1.0, v2
	s_waitcnt lgkmcnt(0)
	v_mul_f32_e32 v0, v2, v42
	v_sub_f32_e32 v51, 1.0, v3
	v_mul_f32_e32 v10, v3, v26
	v_sub_f32_e32 v52, 1.0, v4
	v_mul_f32_e32 v11, v4, v28
	v_mul_f32_e32 v12, v5, v30
	s_waitcnt vmcnt(0)
	v_sub_f32_e32 v54, 1.0, v6
	v_mul_f32_e32 v13, v6, v32
	v_sub_f32_e32 v55, 1.0, v7
	v_mul_f32_e32 v56, v7, v34
	v_sub_f32_e32 v57, 1.0, v8
	v_sub_f32_e32 v59, 1.0, v9
	v_mul_f32_e32 v30, v53, v30
	v_mul_f32_e32 v58, v8, v36
	v_mul_f32_e32 v60, v9, v40
	v_mul_f32_e32 v61, v2, v43
	v_mul_f32_e32 v62, v3, v27
	v_mul_f32_e32 v63, v4, v29
	v_mul_f32_e32 v64, v5, v31
	v_mul_f32_e32 v42, v50, v42
	v_mul_f32_e32 v69, v51, v26
	v_mul_f32_e32 v70, v52, v28
	v_mul_f32_e32 v32, v54, v32
	v_mul_f32_e32 v34, v55, v34
	v_mul_f32_e32 v36, v57, v36
	v_mul_f32_e32 v40, v59, v40
	v_cvt_pk_bf16_f32 v10, v0, v10
	v_cvt_pk_bf16_f32 v11, v11, v12
	v_cvt_pk_bf16_f32 v12, v13, v56
	v_cvt_pk_bf16_f32 v13, v58, v60
	v_mul_f32_e32 v0, v50, v43
	v_mul_f32_e32 v27, v51, v27
	v_mul_f32_e32 v43, v52, v29
	v_mul_f32_e32 v56, v53, v31
	v_cvt_pk_bf16_f32 v28, v42, v69
	v_cvt_pk_bf16_f32 v29, v70, v30
	v_cvt_pk_bf16_f32 v30, v32, v34
	v_cvt_pk_bf16_f32 v31, v36, v40
	v_mul_f32_e32 v65, v6, v33
	v_mul_f32_e32 v66, v7, v35
	v_mul_f32_e32 v67, v8, v37
	v_mul_f32_e32 v68, v9, v41
	v_mul_f32_e32 v33, v54, v33
	v_mul_f32_e32 v35, v55, v35
	v_mul_f32_e32 v37, v57, v37
	v_mul_f32_e32 v41, v59, v41
	v_cvt_pk_bf16_f32 v26, v61, v62
	global_store_dwordx4 v[46:47], v[10:13], off offset:2048 nt
	s_nop 1
	v_cvt_pk_bf16_f32 v10, v0, v27
	v_cvt_pk_bf16_f32 v11, v43, v56
	v_cvt_pk_bf16_f32 v12, v33, v35
	v_cvt_pk_bf16_f32 v13, v37, v41
	global_store_dwordx4 v[46:47], v[28:31], off nt
	global_store_dwordx4 v[48:49], v[10:13], off nt
	v_cvt_pk_bf16_f32 v27, v63, v64
	v_or_b32_e32 v0, s1, v38
	v_cvt_pk_bf16_f32 v28, v65, v66
	v_cvt_pk_bf16_f32 v29, v67, v68
	global_store_dwordx4 v[48:49], v[26:29], off offset:2048 nt
	ds_read2_b32 v[26:27], v19 offset0:16 offset1:24
	ds_read2_b32 v[28:29], v19 offset0:49 offset1:57
	ds_read2_b32 v[30:31], v19 offset0:82 offset1:90
	ds_read2_b32 v[32:33], v19 offset0:115 offset1:123
	ds_read2_b32 v[34:35], v19 offset0:148 offset1:156
	ds_read2_b32 v[36:37], v19 offset0:181 offset1:189
	ds_read2_b32 v[40:41], v19 offset0:214 offset1:222
	ds_read2_b32 v[42:43], v19 offset0:247 offset1:255
	v_lshlrev_b32_e32 v0, 12, v0
	v_lshl_add_u64 v[46:47], v[44:45], 0, v[0:1]
	s_waitcnt lgkmcnt(7)
	v_mul_f32_e32 v0, v50, v26
	s_waitcnt lgkmcnt(6)
	v_mul_f32_e32 v10, v51, v28
	s_waitcnt lgkmcnt(5)
	v_mul_f32_e32 v11, v52, v30
	s_waitcnt lgkmcnt(4)
	v_mul_f32_e32 v12, v53, v32
	s_waitcnt lgkmcnt(3)
	v_mul_f32_e32 v13, v54, v34
	s_waitcnt lgkmcnt(2)
	v_mul_f32_e32 v48, v55, v36
	s_waitcnt lgkmcnt(1)
	v_mul_f32_e32 v49, v57, v40
	s_waitcnt lgkmcnt(0)
	v_mul_f32_e32 v56, v59, v42
	v_cvt_pk_bf16_f32 v10, v0, v10
	v_cvt_pk_bf16_f32 v11, v11, v12
	v_cvt_pk_bf16_f32 v12, v13, v48
	v_cvt_pk_bf16_f32 v13, v49, v56
	v_or_b32_e32 v0, s1, v39
	v_mul_f32_e32 v26, v2, v26
	v_mul_f32_e32 v28, v3, v28
	v_mul_f32_e32 v30, v4, v30
	v_mul_f32_e32 v32, v5, v32
	v_mul_f32_e32 v34, v6, v34
	v_mul_f32_e32 v36, v7, v36
	v_mul_f32_e32 v40, v8, v40
	v_mul_f32_e32 v42, v9, v42
	global_store_dwordx4 v[46:47], v[10:13], off nt
	v_lshlrev_b32_e32 v0, 12, v0
	v_mul_f32_e32 v6, v6, v35
	v_cvt_pk_bf16_f32 v10, v26, v28
	v_cvt_pk_bf16_f32 v11, v30, v32
	v_cvt_pk_bf16_f32 v12, v34, v36
	v_cvt_pk_bf16_f32 v13, v40, v42
	global_store_dwordx4 v[46:47], v[10:13], off offset:2048 nt
	v_mul_f32_e32 v26, v4, v31
	v_mul_f32_e32 v4, v53, v33
	v_lshl_add_u64 v[10:11], v[44:45], 0, v[0:1]
	v_mul_f32_e32 v0, v50, v27
	v_mul_f32_e32 v12, v2, v27
	v_mul_f32_e32 v2, v51, v29
	v_mul_f32_e32 v13, v3, v29
	v_mul_f32_e32 v3, v52, v31
	v_mul_f32_e32 v27, v5, v33
	v_mul_f32_e32 v5, v54, v35
	v_mul_f32_e32 v28, v55, v37
	v_mul_f32_e32 v29, v57, v41
	v_mul_f32_e32 v30, v59, v43
	v_cvt_pk_bf16_f32 v2, v0, v2
	v_cvt_pk_bf16_f32 v3, v3, v4
	v_cvt_pk_bf16_f32 v4, v5, v28
	v_cvt_pk_bf16_f32 v5, v29, v30
	v_mul_f32_e32 v7, v7, v37
	v_mul_f32_e32 v8, v8, v41
	v_mul_f32_e32 v9, v9, v43
	global_store_dwordx4 v[10:11], v[2:5], off nt
	s_nop 1
	v_cvt_pk_bf16_f32 v2, v12, v13
	v_cvt_pk_bf16_f32 v3, v26, v27
	v_cvt_pk_bf16_f32 v4, v6, v7
	v_cvt_pk_bf16_f32 v5, v8, v9
	global_store_dwordx4 v[10:11], v[2:5], off offset:2048 nt
	s_waitcnt lgkmcnt(0)

; __device__ __forceinline__ void tr_item(const float* __restrict__ W, int ldw, int k0, int n0, bf16* __restrict__ WT, int ldt, int drow, const float* __restrict__ mu, LAS float* scr, int lane, const float* __restrict__ gs = nullptr) {
; #pragma unroll 8
;     for (int i = 0; i < 32; ++i) { const int kk = 2 * i + (lane >> 5); scr[kk * 33 + (lane & 31)] = W[(size_t)(k0 + kk) * ldw + n0 + (lane & 31)]; }
.LBB0_1460:
	s_lshl_b32 s9, s7, 1
	s_lshl_b32 s10, s8, 1
	v_or_b32_e32 v41, s10, v14
	s_add_i32 s11, s9, 4
	s_add_i32 s12, s10, 4
	s_add_i32 s14, s10, 8
	v_add_u32_e32 v0, s0, v41
	v_or_b32_e32 v42, s11, v15
	v_or_b32_e32 v43, s12, v14
	v_mov_b32_e32 v7, v1
	v_or_b32_e32 v40, s9, v15
	s_add_i32 s16, s10, 12
	v_or_b32_e32 v45, s14, v14
	s_waitcnt lgkmcnt(3)
	v_lshlrev_b64 v[32:33], 8, v[0:1]
	v_add_u32_e32 v6, s5, v42
	v_add_u32_e32 v0, s0, v43
	v_mov_b32_e32 v5, v1
	s_add_i32 s13, s9, 8
	s_add_i32 s15, s9, 12
	s_add_i32 s18, s10, 16
	v_add_u32_e32 v4, s5, v40
	v_or_b32_e32 v47, s16, v14
	v_lshlrev_b64 v[6:7], 8, v[6:7]
	v_lshlrev_b64 v[34:35], 8, v[0:1]
	v_add_u32_e32 v0, s0, v45
	s_add_i32 s20, s10, 20
	v_or_b32_e32 v44, s13, v15
	v_or_b32_e32 v46, s15, v15
	v_or_b32_e32 v49, s18, v14
	v_lshlrev_b64 v[4:5], 8, v[4:5]
	v_lshl_add_u64 v[32:33], v[2:3], 0, v[32:33]
	v_lshl_add_u64 v[6:7], v[2:3], 0, v[6:7]
	v_lshlrev_b64 v[36:37], 8, v[0:1]
	v_add_u32_e32 v0, s0, v47
	v_mov_b32_e32 v9, v1
	v_mov_b32_e32 v11, v1
	s_add_i32 s17, s9, 16
	s_add_i32 s19, s9, 20
	s_add_i32 s22, s10, 24
	v_or_b32_e32 v51, s20, v14
	v_add_u32_e32 v8, s5, v44
	v_add_u32_e32 v10, s5, v46
	v_lshl_add_u64 v[4:5], v[2:3], 0, v[4:5]
	v_lshl_add_u64 v[34:35], v[2:3], 0, v[34:35]
	global_load_dword v56, v[32:33], off nt
	global_load_dword v57, v[4:5], off nt
	global_load_dword v58, v[34:35], off nt
	global_load_dword v59, v[6:7], off nt
	v_lshlrev_b64 v[6:7], 8, v[0:1]
	v_add_u32_e32 v0, s0, v49
	s_add_i32 s21, s9, 24
	s_add_i32 s9, s9, 28
	s_add_i32 s10, s10, 28
	v_or_b32_e32 v48, s17, v15
	v_or_b32_e32 v50, s19, v15
	v_or_b32_e32 v53, s22, v14
	v_lshlrev_b64 v[8:9], 8, v[8:9]
	v_lshlrev_b64 v[10:11], 8, v[10:11]
	v_lshl_add_u64 v[4:5], v[2:3], 0, v[36:37]
	v_lshl_add_u64 v[6:7], v[2:3], 0, v[6:7]
	v_lshlrev_b64 v[32:33], 8, v[0:1]
	v_add_u32_e32 v0, s0, v51
	s_waitcnt lgkmcnt(0)
	v_mov_b32_e32 v13, v1
	v_mov_b32_e32 v27, v1
	v_or_b32_e32 v52, s21, v15
	v_or_b32_e32 v54, s9, v15
	v_or_b32_e32 v55, s10, v14
	v_add_u32_e32 v12, s5, v48
	v_add_u32_e32 v26, s5, v50
	v_lshl_add_u64 v[8:9], v[2:3], 0, v[8:9]
	v_lshl_add_u64 v[10:11], v[2:3], 0, v[10:11]
	global_load_dword v60, v[4:5], off nt
	global_load_dword v61, v[8:9], off nt
	global_load_dword v62, v[6:7], off nt
	global_load_dword v63, v[10:11], off nt
	v_lshlrev_b64 v[6:7], 8, v[0:1]
	v_add_u32_e32 v0, s0, v53
	v_mov_b32_e32 v29, v1
	v_mov_b32_e32 v31, v1
	v_add_u32_e32 v28, s5, v52
	v_add_u32_e32 v30, s5, v54
	v_lshlrev_b64 v[12:13], 8, v[12:13]
	v_lshlrev_b64 v[26:27], 8, v[26:27]
	v_lshl_add_u64 v[4:5], v[2:3], 0, v[32:33]
	v_lshl_add_u64 v[6:7], v[2:3], 0, v[6:7]
	v_lshlrev_b64 v[8:9], 8, v[0:1]
	v_add_u32_e32 v0, s0, v55
	v_lshlrev_b64 v[28:29], 8, v[28:29]
	v_lshlrev_b64 v[30:31], 8, v[30:31]
	v_lshl_add_u64 v[12:13], v[2:3], 0, v[12:13]
	v_lshl_add_u64 v[26:27], v[2:3], 0, v[26:27]
	global_load_dword v64, v[4:5], off nt
	global_load_dword v65, v[12:13], off nt
	global_load_dword v66, v[6:7], off nt
	global_load_dword v67, v[26:27], off nt
	v_lshl_add_u64 v[4:5], v[2:3], 0, v[8:9]
	v_lshlrev_b64 v[6:7], 8, v[0:1]
	v_lshl_add_u64 v[28:29], v[2:3], 0, v[28:29]
	v_lshl_add_u64 v[30:31], v[2:3], 0, v[30:31]
	v_lshl_add_u64 v[6:7], v[2:3], 0, v[6:7]
	global_load_dword v0, v[4:5], off nt
	global_load_dword v68, v[28:29], off nt
	global_load_dword v69, v[6:7], off nt
	global_load_dword v70, v[30:31], off nt
	s_add_i32 s8, s8, 16
	s_add_i32 s7, s7, 16
	s_add_i32 s4, s4, -16
	v_mad_u64_u32 v[4:5], s[10:11], v41, s26, v[18:19]
	s_cmp_lg_u32 s4, 0
	v_mad_u64_u32 v[6:7], s[10:11], v40, s26, v[18:19]
	v_mad_u64_u32 v[8:9], s[10:11], v43, s26, v[18:19]
	v_mad_u64_u32 v[10:11], s[10:11], v42, s26, v[18:19]
	v_mad_u64_u32 v[12:13], s[10:11], v45, s26, v[18:19]
	v_mad_u64_u32 v[26:27], s[10:11], v44, s26, v[18:19]
	v_mad_u64_u32 v[28:29], s[10:11], v47, s26, v[18:19]
	v_mad_u64_u32 v[30:31], s[10:11], v46, s26, v[18:19]
	v_mad_u64_u32 v[32:33], s[10:11], v49, s26, v[18:19]
	v_mad_u64_u32 v[34:35], s[10:11], v48, s26, v[18:19]
	v_mad_u64_u32 v[36:37], s[10:11], v51, s26, v[18:19]
	v_mad_u64_u32 v[40:41], s[10:11], v50, s26, v[18:19]
	v_mad_u64_u32 v[42:43], s[10:11], v53, s26, v[18:19]
	v_mad_u64_u32 v[44:45], s[10:11], v52, s26, v[18:19]
	v_mad_u64_u32 v[46:47], s[10:11], v55, s26, v[18:19]
	v_mad_u64_u32 v[48:49], s[10:11], v54, s26, v[18:19]
	s_waitcnt vmcnt(15)
	ds_write_b32 v4, v56
	s_waitcnt vmcnt(14)
	ds_write_b32 v6, v57
	s_waitcnt vmcnt(13)
	ds_write_b32 v8, v58
	s_waitcnt vmcnt(12)
	ds_write_b32 v10, v59
	s_waitcnt vmcnt(11)
	ds_write_b32 v12, v60
	s_waitcnt vmcnt(10)
	ds_write_b32 v26, v61
	s_waitcnt vmcnt(9)
	ds_write_b32 v28, v62
	s_waitcnt vmcnt(8)
	ds_write_b32 v30, v63
	s_waitcnt vmcnt(7)
	ds_write_b32 v32, v64
	s_waitcnt vmcnt(6)
	ds_write_b32 v34, v65
	s_waitcnt vmcnt(5)
	ds_write_b32 v36, v66
	s_waitcnt vmcnt(4)
	ds_write_b32 v40, v67
	s_waitcnt vmcnt(3)
	ds_write_b32 v42, v0
	s_waitcnt vmcnt(2)
	ds_write_b32 v44, v68
	s_waitcnt vmcnt(1)
	ds_write_b32 v46, v69
	s_waitcnt vmcnt(0)
	ds_write_b32 v48, v70
	s_cbranch_scc1 .LBB0_1460
; #define LAS __attribute__((address_space(3)))
; __device__ __forceinline__ v4u pack8(const float (&f)[8]) { v4u w; w.x = cvt_pk_bf16(f[0], f[1]); w.y = cvt_pk_bf16(f[2], f[3]); w.z = cvt_pk_bf16(f[4], f[5]); w.w = cvt_pk_bf16(f[6], f[7]); return w; }
; __device__ __forceinline__ void tr_item(const float* __restrict__ W, int ldw, int k0, int n0, bf16* __restrict__ WT, int ldt, int drow, const float* __restrict__ mu, LAS float* scr, int lane, const float* __restrict__ gs = nullptr) {
;     ...
;     if (mu) {
; #pragma unroll
;         for (int e = 0; e < 8; ++e) mv[e] = mu[k0 + 8 * c + e];
;     } else if (gs) {
; #pragma unroll
;         for (int e = 0; e < 8; ++e) mv[e] = gs[k0 + 8 * c + e];
;     }
; #pragma unroll
;     for (int j = 0; j < 4; ++j) {
;         const int n = (lane >> 3) + 8 * j; const LAS float* s = scr + (8 * c) * 33 + n;
;         float f[8];
; #pragma unroll
;         for (int e = 0; e < 8; ++e) f[e] = s[e * 33];
;         bf16* dp = WT + (size_t)(drow + n) * ldt + k0 + 8 * c;
;         if (mu) {
;             float f1[8], f2[8];
; #pragma unroll
;             for (int e = 0; e < 8; ++e) { f1[e] = f[e] * (1.f - mv[e]); f2[e] = f[e] * mv[e]; }
;             *(v4u*)dp = pack8(f1); *(v4u*)(dp + 1024) = pack8(f2);
	s_mul_i32 s7, s94, 6
	s_mul_hi_u32 s4, s94, 0xe00000
	s_mul_i32 s5, s94, 0xe00000
	s_or_b32 s94, s7, 1
	s_add_u32 s7, s36, s5
	s_addc_u32 s8, s37, s4
	s_lshl_b64 s[4:5], s[94:95], 12
	s_or_b32 s1, s1, 0xc00
	s_add_u32 s4, s50, s4
	v_or_b32_e32 v0, s0, v20
	s_addc_u32 s5, s51, s5
	s_waitcnt lgkmcnt(0)
	v_lshlrev_b32_e32 v0, 2, v0
	global_load_dwordx4 v[2:5], v0, s[4:5]
	global_load_dwordx4 v[6:9], v0, s[4:5] offset:16
	ds_read2_b32 v[26:27], v19 offset0:33 offset1:41
	ds_read2_b32 v[28:29], v19 offset0:66 offset1:74
	ds_read2_b32 v[30:31], v19 offset0:99 offset1:107
	ds_read2_b32 v[32:33], v19 offset0:132 offset1:140
	ds_read2_b32 v[34:35], v19 offset0:165 offset1:173
	ds_read2_b32 v[36:37], v19 offset0:198 offset1:206
	ds_read2_b32 v[40:41], v19 offset0:231 offset1:239
	ds_read2_b32 v[42:43], v19 offset1:8
	s_lshl_b32 s0, s0, 1
	s_add_u32 s4, s7, s0
	v_lshlrev_b32_e32 v0, 1, v20
	v_or_b32_e32 v10, s1, v17
	s_addc_u32 s5, s8, 0
	v_or_b32_e32 v11, s1, v21
	v_lshl_add_u64 v[44:45], s[4:5], 0, v[0:1]
	v_lshlrev_b32_e32 v0, 12, v10
	v_lshl_add_u64 v[46:47], v[44:45], 0, v[0:1]
	v_lshlrev_b32_e32 v0, 12, v11
	v_lshl_add_u64 v[48:49], v[44:45], 0, v[0:1]
	s_waitcnt vmcnt(1)
	v_sub_f32_e32 v53, 1.0, v5
	v_sub_f32_e32 v50, 1.0, v2
	s_waitcnt lgkmcnt(0)
	v_mul_f32_e32 v0, v2, v42
	v_sub_f32_e32 v51, 1.0, v3
	v_mul_f32_e32 v10, v3, v26
	v_sub_f32_e32 v52, 1.0, v4
	v_mul_f32_e32 v11, v4, v28
	v_mul_f32_e32 v12, v5, v30
	s_waitcnt vmcnt(0)
	v_sub_f32_e32 v54, 1.0, v6
	v_mul_f32_e32 v13, v6, v32
	v_sub_f32_e32 v55, 1.0, v7
	v_mul_f32_e32 v56, v7, v34
	v_sub_f32_e32 v57, 1.0, v8
	v_sub_f32_e32 v59, 1.0, v9
	v_mul_f32_e32 v30, v53, v30
	v_mul_f32_e32 v58, v8, v36
	v_mul_f32_e32 v60, v9, v40
	v_mul_f32_e32 v61, v2, v43
	v_mul_f32_e32 v62, v3, v27
	v_mul_f32_e32 v63, v4, v29
	v_mul_f32_e32 v64, v5, v31
	v_mul_f32_e32 v42, v50, v42
	v_mul_f32_e32 v69, v51, v26
	v_mul_f32_e32 v70, v52, v28
	v_mul_f32_e32 v32, v54, v32
	v_mul_f32_e32 v34, v55, v34
	v_mul_f32_e32 v36, v57, v36
	v_mul_f32_e32 v40, v59, v40
	v_cvt_pk_bf16_f32 v10, v0, v10
	v_cvt_pk_bf16_f32 v11, v11, v12
	v_cvt_pk_bf16_f32 v12, v13, v56
	v_cvt_pk_bf16_f32 v13, v58, v60
	v_mul_f32_e32 v0, v50, v43
	v_mul_f32_e32 v27, v51, v27
	v_mul_f32_e32 v43, v52, v29
	v_mul_f32_e32 v56, v53, v31
	v_cvt_pk_bf16_f32 v28, v42, v69
	v_cvt_pk_bf16_f32 v29, v70, v30
	v_cvt_pk_bf16_f32 v30, v32, v34
	v_cvt_pk_bf16_f32 v31, v36, v40
	v_mul_f32_e32 v65, v6, v33
	v_mul_f32_e32 v66, v7, v35
	v_mul_f32_e32 v67, v8, v37
	v_mul_f32_e32 v68, v9, v41
	v_mul_f32_e32 v33, v54, v33
	v_mul_f32_e32 v35, v55, v35
	v_mul_f32_e32 v37, v57, v37
	v_mul_f32_e32 v41, v59, v41
	v_cvt_pk_bf16_f32 v26, v61, v62
	global_store_dwordx4 v[46:47], v[10:13], off offset:2048 nt
	s_nop 1
	v_cvt_pk_bf16_f32 v10, v0, v27
	v_cvt_pk_bf16_f32 v11, v43, v56
	v_cvt_pk_bf16_f32 v12, v33, v35
	v_cvt_pk_bf16_f32 v13, v37, v41
	global_store_dwordx4 v[46:47], v[28:31], off nt
	global_store_dwordx4 v[48:49], v[10:13], off nt
	v_cvt_pk_bf16_f32 v27, v63, v64
	v_or_b32_e32 v0, s1, v38
	v_cvt_pk_bf16_f32 v28, v65, v66
	v_cvt_pk_bf16_f32 v29, v67, v68
	global_store_dwordx4 v[48:49], v[26:29], off offset:2048 nt
	ds_read2_b32 v[26:27], v19 offset0:16 offset1:24
	ds_read2_b32 v[28:29], v19 offset0:49 offset1:57
	ds_read2_b32 v[30:31], v19 offset0:82 offset1:90
	ds_read2_b32 v[32:33], v19 offset0:115 offset1:123
	ds_read2_b32 v[34:35], v19 offset0:148 offset1:156
	ds_read2_b32 v[36:37], v19 offset0:181 offset1:189
	ds_read2_b32 v[40:41], v19 offset0:214 offset1:222
	ds_read2_b32 v[42:43], v19 offset0:247 offset1:255
	v_lshlrev_b32_e32 v0, 12, v0
	v_lshl_add_u64 v[46:47], v[44:45], 0, v[0:1]
	s_waitcnt lgkmcnt(7)
	v_mul_f32_e32 v0, v50, v26
	s_waitcnt lgkmcnt(6)
	v_mul_f32_e32 v10, v51, v28
	s_waitcnt lgkmcnt(5)
	v_mul_f32_e32 v11, v52, v30
	s_waitcnt lgkmcnt(4)
	v_mul_f32_e32 v12, v53, v32
	s_waitcnt lgkmcnt(3)
	v_mul_f32_e32 v13, v54, v34
	s_waitcnt lgkmcnt(2)
	v_mul_f32_e32 v48, v55, v36
	s_waitcnt lgkmcnt(1)
	v_mul_f32_e32 v49, v57, v40
	s_waitcnt lgkmcnt(0)
	v_mul_f32_e32 v56, v59, v42
	v_cvt_pk_bf16_f32 v10, v0, v10
	v_cvt_pk_bf16_f32 v11, v11, v12
	v_cvt_pk_bf16_f32 v12, v13, v48
	v_cvt_pk_bf16_f32 v13, v49, v56
	v_or_b32_e32 v0, s1, v39
	v_mul_f32_e32 v26, v2, v26
	v_mul_f32_e32 v28, v3, v28
	v_mul_f32_e32 v30, v4, v30
	v_mul_f32_e32 v32, v5, v32
	v_mul_f32_e32 v34, v6, v34
	v_mul_f32_e32 v36, v7, v36
	v_mul_f32_e32 v40, v8, v40
	v_mul_f32_e32 v42, v9, v42
	global_store_dwordx4 v[46:47], v[10:13], off nt
	v_lshlrev_b32_e32 v0, 12, v0
	v_mul_f32_e32 v6, v6, v35
	v_cvt_pk_bf16_f32 v10, v26, v28
	v_cvt_pk_bf16_f32 v11, v30, v32
	v_cvt_pk_bf16_f32 v12, v34, v36
	v_cvt_pk_bf16_f32 v13, v40, v42
	global_store_dwordx4 v[46:47], v[10:13], off offset:2048 nt
	v_mul_f32_e32 v26, v4, v31
	v_mul_f32_e32 v4, v53, v33
	v_lshl_add_u64 v[10:11], v[44:45], 0, v[0:1]
	v_mul_f32_e32 v0, v50, v27
	v_mul_f32_e32 v12, v2, v27
	v_mul_f32_e32 v2, v51, v29
	v_mul_f32_e32 v13, v3, v29
	v_mul_f32_e32 v3, v52, v31
	v_mul_f32_e32 v27, v5, v33
	v_mul_f32_e32 v5, v54, v35
	v_mul_f32_e32 v28, v55, v37
	v_mul_f32_e32 v29, v57, v41
	v_mul_f32_e32 v30, v59, v43
	v_cvt_pk_bf16_f32 v2, v0, v2
	v_cvt_pk_bf16_f32 v3, v3, v4
	v_cvt_pk_bf16_f32 v4, v5, v28
	v_cvt_pk_bf16_f32 v5, v29, v30
	v_mul_f32_e32 v7, v7, v37
	v_mul_f32_e32 v8, v8, v41
	v_mul_f32_e32 v9, v9, v43
	global_store_dwordx4 v[10:11], v[2:5], off nt
	s_nop 1
	v_cvt_pk_bf16_f32 v2, v12, v13
	v_cvt_pk_bf16_f32 v3, v26, v27
	v_cvt_pk_bf16_f32 v4, v6, v7
	v_cvt_pk_bf16_f32 v5, v8, v9
	global_store_dwordx4 v[10:11], v[2:5], off offset:2048 nt
	s_waitcnt lgkmcnt(0)

; __device__ __forceinline__ void tr_item(const float* __restrict__ W, int ldw, int k0, int n0, bf16* __restrict__ WT, int ldt, int drow, const float* __restrict__ mu, LAS float* scr, int lane, const float* __restrict__ gs = nullptr) {
; #pragma unroll 8
;     for (int i = 0; i < 32; ++i) { const int kk = 2 * i + (lane >> 5); scr[kk * 33 + (lane & 31)] = W[(size_t)(k0 + kk) * ldw + n0 + (lane & 31)]; }
;     asm volatile("s_waitcnt lgkmcnt(0)" ::: "memory");
;     const int c = lane & 7;
;     float mv[8];
;     if (mu) {
; #pragma unroll
;         for (int e = 0; e < 8; ++e) mv[e] = mu[k0 + 8 * c + e];
.LBB0_1465:
	s_lshl_b32 s13, s1, 1
	s_lshl_b32 s14, s0, 1
	v_or_b32_e32 v41, s14, v14
	s_add_i32 s15, s13, 4
	s_add_i32 s16, s14, 4
	s_add_i32 s18, s14, 8
	v_add_u32_e32 v0, s8, v41
	v_or_b32_e32 v42, s15, v15
	v_or_b32_e32 v43, s16, v14
	v_mov_b32_e32 v7, v1
	v_or_b32_e32 v40, s13, v15
	s_add_i32 s20, s14, 12
	v_or_b32_e32 v45, s18, v14
	s_waitcnt lgkmcnt(3)
	v_lshlrev_b64 v[32:33], 12, v[0:1]
	v_add_u32_e32 v6, s11, v42
	v_add_u32_e32 v0, s8, v43
	v_mov_b32_e32 v5, v1
	s_add_i32 s17, s13, 8
	s_add_i32 s19, s13, 12
	s_add_i32 s22, s14, 16
	v_add_u32_e32 v4, s11, v40
	v_or_b32_e32 v47, s20, v14
	v_lshlrev_b64 v[6:7], 12, v[6:7]
	v_lshlrev_b64 v[34:35], 12, v[0:1]
	v_add_u32_e32 v0, s8, v45
	s_add_i32 s25, s14, 20
	v_or_b32_e32 v44, s17, v15
	v_or_b32_e32 v46, s19, v15
	v_or_b32_e32 v49, s22, v14
	v_lshlrev_b64 v[4:5], 12, v[4:5]
	v_lshl_add_u64 v[32:33], v[2:3], 0, v[32:33]
	v_lshl_add_u64 v[6:7], v[2:3], 0, v[6:7]
	v_lshlrev_b64 v[36:37], 12, v[0:1]
	v_add_u32_e32 v0, s8, v47
	v_mov_b32_e32 v9, v1
	v_mov_b32_e32 v11, v1
	s_add_i32 s21, s13, 16
	s_add_i32 s23, s13, 20
	s_add_i32 s28, s14, 24
	v_or_b32_e32 v51, s25, v14
	v_add_u32_e32 v8, s11, v44
	v_add_u32_e32 v10, s11, v46
	v_lshl_add_u64 v[4:5], v[2:3], 0, v[4:5]
	v_lshl_add_u64 v[34:35], v[2:3], 0, v[34:35]
	global_load_dword v56, v[32:33], off nt
	global_load_dword v57, v[4:5], off nt
	global_load_dword v58, v[34:35], off nt
	global_load_dword v59, v[6:7], off nt
	v_lshlrev_b64 v[6:7], 12, v[0:1]
	v_add_u32_e32 v0, s8, v49
	s_add_i32 s27, s13, 24
	s_add_i32 s13, s13, 28
	s_add_i32 s14, s14, 28
	v_or_b32_e32 v48, s21, v15
	v_or_b32_e32 v50, s23, v15
	v_or_b32_e32 v53, s28, v14
	v_lshlrev_b64 v[8:9], 12, v[8:9]
	v_lshlrev_b64 v[10:11], 12, v[10:11]
	v_lshl_add_u64 v[4:5], v[2:3], 0, v[36:37]
	v_lshl_add_u64 v[6:7], v[2:3], 0, v[6:7]
	v_lshlrev_b64 v[32:33], 12, v[0:1]
	v_add_u32_e32 v0, s8, v51
	s_waitcnt lgkmcnt(0)
	v_mov_b32_e32 v13, v1
	v_mov_b32_e32 v27, v1
	v_or_b32_e32 v52, s27, v15
	v_or_b32_e32 v54, s13, v15
	v_or_b32_e32 v55, s14, v14
	v_add_u32_e32 v12, s11, v48
	v_add_u32_e32 v26, s11, v50
	v_lshl_add_u64 v[8:9], v[2:3], 0, v[8:9]
	v_lshl_add_u64 v[10:11], v[2:3], 0, v[10:11]
	global_load_dword v60, v[4:5], off nt
	global_load_dword v61, v[8:9], off nt
	global_load_dword v62, v[6:7], off nt
	global_load_dword v63, v[10:11], off nt
	v_lshlrev_b64 v[6:7], 12, v[0:1]
	v_add_u32_e32 v0, s8, v53
	v_mov_b32_e32 v29, v1
	v_mov_b32_e32 v31, v1
	v_add_u32_e32 v28, s11, v52
	v_add_u32_e32 v30, s11, v54
	v_lshlrev_b64 v[12:13], 12, v[12:13]
	v_lshlrev_b64 v[26:27], 12, v[26:27]
	v_lshl_add_u64 v[4:5], v[2:3], 0, v[32:33]
	v_lshl_add_u64 v[6:7], v[2:3], 0, v[6:7]
	v_lshlrev_b64 v[8:9], 12, v[0:1]
	v_add_u32_e32 v0, s8, v55
	v_lshlrev_b64 v[28:29], 12, v[28:29]
	v_lshlrev_b64 v[30:31], 12, v[30:31]
	v_lshl_add_u64 v[12:13], v[2:3], 0, v[12:13]
	v_lshl_add_u64 v[26:27], v[2:3], 0, v[26:27]
	global_load_dword v64, v[4:5], off nt
	global_load_dword v65, v[12:13], off nt
	global_load_dword v66, v[6:7], off nt
	global_load_dword v67, v[26:27], off nt
	v_lshl_add_u64 v[4:5], v[2:3], 0, v[8:9]
	v_lshlrev_b64 v[6:7], 12, v[0:1]
	v_lshl_add_u64 v[28:29], v[2:3], 0, v[28:29]
	v_lshl_add_u64 v[30:31], v[2:3], 0, v[30:31]
	v_lshl_add_u64 v[6:7], v[2:3], 0, v[6:7]
	global_load_dword v0, v[4:5], off nt
	global_load_dword v68, v[28:29], off nt
	global_load_dword v69, v[6:7], off nt
	global_load_dword v70, v[30:31], off nt
	s_add_i32 s0, s0, 16
	s_add_i32 s1, s1, 16
	s_add_i32 s12, s12, -16
	v_mad_u64_u32 v[4:5], s[14:15], v41, s26, v[18:19]
	s_cmp_lg_u32 s12, 0
	v_mad_u64_u32 v[6:7], s[14:15], v40, s26, v[18:19]
	v_mad_u64_u32 v[8:9], s[14:15], v43, s26, v[18:19]
	v_mad_u64_u32 v[10:11], s[14:15], v42, s26, v[18:19]
	v_mad_u64_u32 v[12:13], s[14:15], v45, s26, v[18:19]
	v_mad_u64_u32 v[26:27], s[14:15], v44, s26, v[18:19]
	v_mad_u64_u32 v[28:29], s[14:15], v47, s26, v[18:19]
	v_mad_u64_u32 v[30:31], s[14:15], v46, s26, v[18:19]
	v_mad_u64_u32 v[32:33], s[14:15], v49, s26, v[18:19]
	v_mad_u64_u32 v[34:35], s[14:15], v48, s26, v[18:19]
	v_mad_u64_u32 v[36:37], s[14:15], v51, s26, v[18:19]
	v_mad_u64_u32 v[40:41], s[14:15], v50, s26, v[18:19]
	v_mad_u64_u32 v[42:43], s[14:15], v53, s26, v[18:19]
	v_mad_u64_u32 v[44:45], s[14:15], v52, s26, v[18:19]
	v_mad_u64_u32 v[46:47], s[14:15], v55, s26, v[18:19]
	v_mad_u64_u32 v[48:49], s[14:15], v54, s26, v[18:19]
	s_waitcnt vmcnt(15)
	ds_write_b32 v4, v56
	s_waitcnt vmcnt(14)
	ds_write_b32 v6, v57
	s_waitcnt vmcnt(13)
	ds_write_b32 v8, v58
	s_waitcnt vmcnt(12)
	ds_write_b32 v10, v59
	s_waitcnt vmcnt(11)
	ds_write_b32 v12, v60
	s_waitcnt vmcnt(10)
	ds_write_b32 v26, v61
	s_waitcnt vmcnt(9)
	ds_write_b32 v28, v62
	s_waitcnt vmcnt(8)
	ds_write_b32 v30, v63
	s_waitcnt vmcnt(7)
	ds_write_b32 v32, v64
	s_waitcnt vmcnt(6)
	ds_write_b32 v34, v65
	s_waitcnt vmcnt(5)
	ds_write_b32 v36, v66
	s_waitcnt vmcnt(4)
	ds_write_b32 v40, v67
	s_waitcnt vmcnt(3)
	ds_write_b32 v42, v0
	s_waitcnt vmcnt(2)
	ds_write_b32 v44, v68
	s_waitcnt vmcnt(1)
	ds_write_b32 v46, v69
	s_waitcnt vmcnt(0)
	ds_write_b32 v48, v70
	s_cbranch_scc1 .LBB0_1465
	v_readlane_b32 s12, v253, 16
	v_readlane_b32 s13, v253, 17
	s_waitcnt lgkmcnt(0)
	s_andn2_b64 vcc, exec, s[12:13]
	s_nop 0
	v_cndmask_b32_e64 v0, 0, 1, s[12:13]
	v_cmp_ne_u32_e64 s[0:1], 1, v0
	s_cbranch_vccnz .LBB0_1469
	s_cmp_eq_u32 s7, 1
	s_cselect_b32 s11, 2, 3
	s_cmpk_gt_u32 s10, 0x1ff
	s_cselect_b32 s12, s11, 0
	s_and_b64 s[10:11], s[4:5], exec
	s_cselect_b32 s10, 6, 0
	s_add_i32 s12, s12, s10
	s_lshl_b32 s10, s12, 12
	s_add_u32 s10, s50, s10
	v_or_b32_e32 v0, s8, v20
	s_addc_u32 s11, s51, 0
	v_lshlrev_b32_e32 v0, 2, v0
	global_load_dwordx4 v[2:5], v0, s[10:11]
	global_load_dwordx4 v[6:9], v0, s[10:11] offset:16
	s_branch .LBB0_1470

; #define LAS __attribute__((address_space(3)))
; __device__ __forceinline__ v4u pack8(const float (&f)[8]) { v4u w; w.x = cvt_pk_bf16(f[0], f[1]); w.y = cvt_pk_bf16(f[2], f[3]); w.z = cvt_pk_bf16(f[4], f[5]); w.w = cvt_pk_bf16(f[6], f[7]); return w; }
; __device__ __forceinline__ void tr_item(const float* __restrict__ W, int ldw, int k0, int n0, bf16* __restrict__ WT, int ldt, int drow, const float* __restrict__ mu, LAS float* scr, int lane, const float* __restrict__ gs = nullptr) {
;     ...
; #pragma unroll
;     for (int j = 0; j < 4; ++j) {
;         const int n = (lane >> 3) + 8 * j; const LAS float* s = scr + (8 * c) * 33 + n;
;         float f[8];
; #pragma unroll
;         for (int e = 0; e < 8; ++e) f[e] = s[e * 33];
;         bf16* dp = WT + (size_t)(drow + n) * ldt + k0 + 8 * c;
;         if (mu) {
;             float f1[8], f2[8];
; #pragma unroll
;             for (int e = 0; e < 8; ++e) { f1[e] = f[e] * (1.f - mv[e]); f2[e] = f[e] * mv[e]; }
;             *(v4u*)dp = pack8(f1); *(v4u*)(dp + 1024) = pack8(f2);
.LBB0_1470:
	s_and_b64 s[4:5], s[4:5], exec
	s_cselect_b32 s4, 0xe00000, 0
	s_lshl_b32 s5, s7, 10
	s_add_u32 s4, s36, s4
	ds_read2_b32 v[36:37], v19 offset1:33
	ds_read2_b32 v[34:35], v19 offset0:66 offset1:99
	ds_read2_b32 v[32:33], v19 offset0:132 offset1:165
	ds_read2_b32 v[30:31], v19 offset0:198 offset1:231
	s_addc_u32 s10, s37, 0
	s_or_b32 s7, s5, s9
	s_lshl_b32 s5, s8, 1
	s_add_u32 s4, s4, s5
	s_addc_u32 s5, s10, 0
	v_lshlrev_b32_e32 v0, 1, v20
	v_lshl_add_u64 v[26:27], s[4:5], 0, v[0:1]
	v_or_b32_e32 v0, s7, v17
	v_lshlrev_b64 v[10:11], 12, v[0:1]
	v_lshl_add_u64 v[28:29], v[26:27], 0, v[10:11]
	s_and_b64 vcc, exec, s[0:1]
	s_waitcnt vmcnt(1)
	v_sub_f32_e32 v47, 1.0, v2
	v_sub_f32_e32 v46, 1.0, v3
	v_sub_f32_e32 v45, 1.0, v4
	v_sub_f32_e32 v44, 1.0, v5
	s_waitcnt vmcnt(0)
	v_sub_f32_e32 v43, 1.0, v6
	v_sub_f32_e32 v42, 1.0, v7
	v_sub_f32_e32 v40, 1.0, v8
	v_sub_f32_e32 v41, 1.0, v9
	s_cbranch_vccnz .LBB0_1493
	s_waitcnt lgkmcnt(3)
	v_mul_f32_e32 v48, v36, v2
	v_mul_f32_e32 v10, v37, v46
	v_mul_f32_e32 v49, v3, v37
	s_waitcnt lgkmcnt(2)
	v_mul_f32_e32 v11, v45, v34
	v_mul_f32_e32 v50, v4, v34
	v_mul_f32_e32 v12, v44, v35
	v_mul_f32_e32 v51, v5, v35
	s_waitcnt lgkmcnt(1)
	v_mul_f32_e32 v13, v43, v32
	v_mul_f32_e32 v0, v36, v47
	v_mul_f32_e32 v52, v6, v32
	v_mul_f32_e32 v53, v42, v33
	v_mul_f32_e32 v54, v7, v33
	s_waitcnt lgkmcnt(0)
	v_mul_f32_e32 v55, v40, v30
	v_mul_f32_e32 v56, v8, v30
	v_mul_f32_e32 v57, v41, v31
	v_mul_f32_e32 v58, v9, v31
	v_cvt_pk_bf16_f32 v10, v0, v10
	v_cvt_pk_bf16_f32 v11, v11, v12
	v_cvt_pk_bf16_f32 v12, v13, v53
	v_cvt_pk_bf16_f32 v13, v55, v57
	v_cvt_pk_bf16_f32 v48, v48, v49
	v_cvt_pk_bf16_f32 v49, v50, v51
	v_cvt_pk_bf16_f32 v50, v52, v54
	v_cvt_pk_bf16_f32 v51, v56, v58
	global_store_dwordx4 v[28:29], v[48:51], off offset:2048 nt
	s_cbranch_execnz .LBB0_1473

; #define LAS __attribute__((address_space(3)))
; __device__ __forceinline__ v4u pack8(const float (&f)[8]) { v4u w; w.x = cvt_pk_bf16(f[0], f[1]); w.y = cvt_pk_bf16(f[2], f[3]); w.z = cvt_pk_bf16(f[4], f[5]); w.w = cvt_pk_bf16(f[6], f[7]); return w; }
; __device__ __forceinline__ void tr_item(const float* __restrict__ W, int ldw, int k0, int n0, bf16* __restrict__ WT, int ldt, int drow, const float* __restrict__ mu, LAS float* scr, int lane, const float* __restrict__ gs = nullptr) {
;     ...
; #pragma unroll
;     for (int j = 0; j < 4; ++j) {
;         const int n = (lane >> 3) + 8 * j; const LAS float* s = scr + (8 * c) * 33 + n;
;         float f[8];
; #pragma unroll
;         for (int e = 0; e < 8; ++e) f[e] = s[e * 33];
;         bf16* dp = WT + (size_t)(drow + n) * ldt + k0 + 8 * c;
;         if (mu) {
;             float f1[8], f2[8];
; #pragma unroll
;             for (int e = 0; e < 8; ++e) { f1[e] = f[e] * (1.f - mv[e]); f2[e] = f[e] * mv[e]; }
;             *(v4u*)dp = pack8(f1); *(v4u*)(dp + 1024) = pack8(f2);
.LBB0_1473:
	global_store_dwordx4 v[28:29], v[10:13], off nt
	s_waitcnt lgkmcnt(3)
	ds_read2_b32 v[36:37], v19 offset0:8 offset1:41
	s_waitcnt lgkmcnt(3)
	ds_read2_b32 v[34:35], v19 offset0:74 offset1:107
	s_waitcnt lgkmcnt(3)
	ds_read2_b32 v[32:33], v19 offset0:140 offset1:173
	s_waitcnt lgkmcnt(3)
	ds_read2_b32 v[30:31], v19 offset0:206 offset1:239
	v_or_b32_e32 v0, s7, v21
	v_lshlrev_b64 v[10:11], 12, v[0:1]
	s_and_b64 vcc, exec, s[0:1]
	v_lshl_add_u64 v[28:29], v[26:27], 0, v[10:11]
	s_cbranch_vccnz .LBB0_1494
	s_waitcnt lgkmcnt(3)
	v_mul_f32_e32 v48, v2, v36
	v_mul_f32_e32 v10, v46, v37
	v_mul_f32_e32 v49, v3, v37
	s_waitcnt lgkmcnt(2)
	v_mul_f32_e32 v11, v45, v34
	v_mul_f32_e32 v50, v4, v34
	v_mul_f32_e32 v12, v44, v35
	v_mul_f32_e32 v51, v5, v35
	s_waitcnt lgkmcnt(1)
	v_mul_f32_e32 v13, v43, v32
	v_mul_f32_e32 v0, v47, v36
	v_mul_f32_e32 v52, v6, v32
	v_mul_f32_e32 v53, v42, v33
	v_mul_f32_e32 v54, v7, v33
	s_waitcnt lgkmcnt(0)
	v_mul_f32_e32 v55, v40, v30
	v_mul_f32_e32 v56, v8, v30
	v_mul_f32_e32 v57, v41, v31
	v_mul_f32_e32 v58, v9, v31
	v_cvt_pk_bf16_f32 v10, v0, v10
	v_cvt_pk_bf16_f32 v11, v11, v12
	v_cvt_pk_bf16_f32 v12, v13, v53
	v_cvt_pk_bf16_f32 v13, v55, v57
	v_cvt_pk_bf16_f32 v48, v48, v49
	v_cvt_pk_bf16_f32 v49, v50, v51
	v_cvt_pk_bf16_f32 v50, v52, v54
	v_cvt_pk_bf16_f32 v51, v56, v58
	global_store_dwordx4 v[28:29], v[48:51], off offset:2048 nt
	s_cbranch_execnz .LBB0_1476

; #define LAS __attribute__((address_space(3)))
; __device__ __forceinline__ v4u pack8(const float (&f)[8]) { v4u w; w.x = cvt_pk_bf16(f[0], f[1]); w.y = cvt_pk_bf16(f[2], f[3]); w.z = cvt_pk_bf16(f[4], f[5]); w.w = cvt_pk_bf16(f[6], f[7]); return w; }
; __device__ __forceinline__ void tr_item(const float* __restrict__ W, int ldw, int k0, int n0, bf16* __restrict__ WT, int ldt, int drow, const float* __restrict__ mu, LAS float* scr, int lane, const float* __restrict__ gs = nullptr) {
;     ...
; #pragma unroll
;     for (int j = 0; j < 4; ++j) {
;         const int n = (lane >> 3) + 8 * j; const LAS float* s = scr + (8 * c) * 33 + n;
;         float f[8];
; #pragma unroll
;         for (int e = 0; e < 8; ++e) f[e] = s[e * 33];
;         bf16* dp = WT + (size_t)(drow + n) * ldt + k0 + 8 * c;
;         if (mu) {
;             float f1[8], f2[8];
; #pragma unroll
;             for (int e = 0; e < 8; ++e) { f1[e] = f[e] * (1.f - mv[e]); f2[e] = f[e] * mv[e]; }
;             *(v4u*)dp = pack8(f1); *(v4u*)(dp + 1024) = pack8(f2);
.LBB0_1476:
	global_store_dwordx4 v[28:29], v[10:13], off nt
	s_waitcnt lgkmcnt(3)
	ds_read2_b32 v[36:37], v19 offset0:16 offset1:49
	s_waitcnt lgkmcnt(3)
	ds_read2_b32 v[34:35], v19 offset0:82 offset1:115
	s_waitcnt lgkmcnt(3)
	ds_read2_b32 v[32:33], v19 offset0:148 offset1:181
	s_waitcnt lgkmcnt(3)
	ds_read2_b32 v[30:31], v19 offset0:214 offset1:247
	v_or_b32_e32 v0, s7, v38
	v_lshlrev_b64 v[10:11], 12, v[0:1]
	s_and_b64 vcc, exec, s[0:1]
	v_lshl_add_u64 v[28:29], v[26:27], 0, v[10:11]
	s_cbranch_vccnz .LBB0_1495
	s_waitcnt lgkmcnt(3)
	v_mul_f32_e32 v48, v2, v36
	v_mul_f32_e32 v10, v46, v37
	v_mul_f32_e32 v49, v3, v37
	s_waitcnt lgkmcnt(2)
	v_mul_f32_e32 v11, v45, v34
	v_mul_f32_e32 v50, v4, v34
	v_mul_f32_e32 v12, v44, v35
	v_mul_f32_e32 v51, v5, v35
	s_waitcnt lgkmcnt(1)
	v_mul_f32_e32 v13, v43, v32
	v_mul_f32_e32 v0, v47, v36
	v_mul_f32_e32 v52, v6, v32
	v_mul_f32_e32 v53, v42, v33
	v_mul_f32_e32 v54, v7, v33
	s_waitcnt lgkmcnt(0)
	v_mul_f32_e32 v55, v40, v30
	v_mul_f32_e32 v56, v8, v30
	v_mul_f32_e32 v57, v41, v31
	v_mul_f32_e32 v58, v9, v31
	v_cvt_pk_bf16_f32 v10, v0, v10
	v_cvt_pk_bf16_f32 v11, v11, v12
	v_cvt_pk_bf16_f32 v12, v13, v53
	v_cvt_pk_bf16_f32 v13, v55, v57
	v_cvt_pk_bf16_f32 v48, v48, v49
	v_cvt_pk_bf16_f32 v49, v50, v51
	v_cvt_pk_bf16_f32 v50, v52, v54
	v_cvt_pk_bf16_f32 v51, v56, v58
	global_store_dwordx4 v[28:29], v[48:51], off offset:2048 nt
	s_cbranch_execnz .LBB0_1479

; #define LAS __attribute__((address_space(3)))
; __device__ __forceinline__ v4u pack8(const float (&f)[8]) { v4u w; w.x = cvt_pk_bf16(f[0], f[1]); w.y = cvt_pk_bf16(f[2], f[3]); w.z = cvt_pk_bf16(f[4], f[5]); w.w = cvt_pk_bf16(f[6], f[7]); return w; }
; __device__ __forceinline__ void tr_item(const float* __restrict__ W, int ldw, int k0, int n0, bf16* __restrict__ WT, int ldt, int drow, const float* __restrict__ mu, LAS float* scr, int lane, const float* __restrict__ gs = nullptr) {
;     ...
; #pragma unroll
;     for (int j = 0; j < 4; ++j) {
;         const int n = (lane >> 3) + 8 * j; const LAS float* s = scr + (8 * c) * 33 + n;
;         float f[8];
; #pragma unroll
;         for (int e = 0; e < 8; ++e) f[e] = s[e * 33];
;         bf16* dp = WT + (size_t)(drow + n) * ldt + k0 + 8 * c;
;         if (mu) {
;             float f1[8], f2[8];
; #pragma unroll
;             for (int e = 0; e < 8; ++e) { f1[e] = f[e] * (1.f - mv[e]); f2[e] = f[e] * mv[e]; }
;             *(v4u*)dp = pack8(f1); *(v4u*)(dp + 1024) = pack8(f2);
.LBB0_1479:
	global_store_dwordx4 v[28:29], v[10:13], off nt
	s_waitcnt lgkmcnt(1)
	ds_read2_b32 v[32:33], v19 offset0:24 offset1:57
	s_waitcnt lgkmcnt(1)
	ds_read2_b32 v[30:31], v19 offset0:90 offset1:123
	ds_read2_b32 v[28:29], v19 offset0:156 offset1:189
	ds_read2_b32 v[12:13], v19 offset0:222 offset1:255
	v_or_b32_e32 v0, s7, v39
	v_lshlrev_b64 v[10:11], 12, v[0:1]
	s_and_b64 vcc, exec, s[0:1]
	v_lshl_add_u64 v[10:11], v[26:27], 0, v[10:11]
	s_cbranch_vccnz .LBB0_1496
	s_waitcnt lgkmcnt(3)
	v_mul_f32_e32 v26, v2, v32
	v_mul_f32_e32 v2, v46, v33
	v_mul_f32_e32 v27, v3, v33
	s_waitcnt lgkmcnt(2)
	v_mul_f32_e32 v3, v45, v30
	v_mul_f32_e32 v34, v4, v30
	v_mul_f32_e32 v4, v44, v31
	v_mul_f32_e32 v35, v5, v31
	s_waitcnt lgkmcnt(1)
	v_mul_f32_e32 v5, v43, v28
	v_mul_f32_e32 v36, v6, v28
	v_mul_f32_e32 v6, v42, v29
	v_mul_f32_e32 v37, v7, v29
	s_waitcnt lgkmcnt(0)
	v_mul_f32_e32 v7, v40, v12
	v_mul_f32_e32 v40, v8, v12
	v_mul_f32_e32 v8, v41, v13
	v_mul_f32_e32 v9, v9, v13
	v_mul_f32_e32 v0, v47, v32
	v_cvt_pk_bf16_f32 v2, v0, v2
	v_cvt_pk_bf16_f32 v3, v3, v4
	v_cvt_pk_bf16_f32 v4, v5, v6
	v_cvt_pk_bf16_f32 v5, v7, v8
	v_cvt_pk_bf16_f32 v6, v26, v27
	v_cvt_pk_bf16_f32 v7, v34, v35
	v_cvt_pk_bf16_f32 v8, v36, v37
	v_cvt_pk_bf16_f32 v9, v40, v9
	global_store_dwordx4 v[10:11], v[6:9], off offset:2048 nt
	s_cbranch_execnz .LBB0_1482

; #define LAS __attribute__((address_space(3)))
; __device__ __forceinline__ v4u pack8(const float (&f)[8]) { v4u w; w.x = cvt_pk_bf16(f[0], f[1]); w.y = cvt_pk_bf16(f[2], f[3]); w.z = cvt_pk_bf16(f[4], f[5]); w.w = cvt_pk_bf16(f[6], f[7]); return w; }
; __device__ __forceinline__ void tr_item(const float* __restrict__ W, int ldw, int k0, int n0, bf16* __restrict__ WT, int ldt, int drow, const float* __restrict__ mu, LAS float* scr, int lane, const float* __restrict__ gs = nullptr) {
;     ...
; #pragma unroll
;     for (int j = 0; j < 4; ++j) {
;         const int n = (lane >> 3) + 8 * j; const LAS float* s = scr + (8 * c) * 33 + n;
;         float f[8];
; #pragma unroll
;         for (int e = 0; e < 8; ++e) f[e] = s[e * 33];
;         bf16* dp = WT + (size_t)(drow + n) * ldt + k0 + 8 * c;
;         if (mu) {
;             float f1[8], f2[8];
; #pragma unroll
;             for (int e = 0; e < 8; ++e) { f1[e] = f[e] * (1.f - mv[e]); f2[e] = f[e] * mv[e]; }
;             *(v4u*)dp = pack8(f1); *(v4u*)(dp + 1024) = pack8(f2);
.LBB0_1482:
	global_store_dwordx4 v[10:11], v[2:5], off nt
	s_waitcnt lgkmcnt(0)

; __device__ __forceinline__ void tr_item(const float* __restrict__ W, int ldw, int k0, int n0, bf16* __restrict__ WT, int ldt, int drow, const float* __restrict__ mu, LAS float* scr, int lane, const float* __restrict__ gs = nullptr) {
; #pragma unroll 8
;     for (int i = 0; i < 32; ++i) { const int kk = 2 * i + (lane >> 5); scr[kk * 33 + (lane & 31)] = W[(size_t)(k0 + kk) * ldw + n0 + (lane & 31)]; }
.LBB0_1486:
	s_lshl_b32 s9, s4, 1
	s_lshl_b32 s10, s7, 1
	v_or_b32_e32 v41, s10, v14
	s_add_i32 s11, s9, 4
	s_add_i32 s12, s10, 4
	s_add_i32 s14, s10, 8
	v_add_u32_e32 v0, s1, v41
	v_or_b32_e32 v42, s11, v15
	v_or_b32_e32 v43, s12, v14
	v_mov_b32_e32 v7, v1
	v_or_b32_e32 v40, s9, v15
	s_add_i32 s16, s10, 12
	v_or_b32_e32 v45, s14, v14
	s_waitcnt lgkmcnt(3)
	v_lshlrev_b64 v[32:33], 12, v[0:1]
	v_add_u32_e32 v6, s5, v42
	v_add_u32_e32 v0, s1, v43
	v_mov_b32_e32 v5, v1
	s_add_i32 s13, s9, 8
	s_add_i32 s15, s9, 12
	s_add_i32 s18, s10, 16
	v_add_u32_e32 v4, s5, v40
	v_or_b32_e32 v47, s16, v14
	v_lshlrev_b64 v[6:7], 12, v[6:7]
	v_lshlrev_b64 v[34:35], 12, v[0:1]
	v_add_u32_e32 v0, s1, v45
	s_add_i32 s20, s10, 20
	v_or_b32_e32 v44, s13, v15
	v_or_b32_e32 v46, s15, v15
	v_or_b32_e32 v49, s18, v14
	v_lshlrev_b64 v[4:5], 12, v[4:5]
	v_lshl_add_u64 v[32:33], v[2:3], 0, v[32:33]
	v_lshl_add_u64 v[6:7], v[2:3], 0, v[6:7]
	v_lshlrev_b64 v[36:37], 12, v[0:1]
	v_add_u32_e32 v0, s1, v47
	v_mov_b32_e32 v9, v1
	v_mov_b32_e32 v11, v1
	s_add_i32 s17, s9, 16
	s_add_i32 s19, s9, 20
	s_add_i32 s22, s10, 24
	v_or_b32_e32 v51, s20, v14
	v_add_u32_e32 v8, s5, v44
	v_add_u32_e32 v10, s5, v46
	v_lshl_add_u64 v[4:5], v[2:3], 0, v[4:5]
	v_lshl_add_u64 v[34:35], v[2:3], 0, v[34:35]
	global_load_dword v56, v[32:33], off nt
	global_load_dword v57, v[4:5], off nt
	global_load_dword v58, v[34:35], off nt
	global_load_dword v59, v[6:7], off nt
	v_lshlrev_b64 v[6:7], 12, v[0:1]
	v_add_u32_e32 v0, s1, v49
	s_add_i32 s21, s9, 24
	s_add_i32 s9, s9, 28
	s_add_i32 s10, s10, 28
	v_or_b32_e32 v48, s17, v15
	v_or_b32_e32 v50, s19, v15
	v_or_b32_e32 v53, s22, v14
	v_lshlrev_b64 v[8:9], 12, v[8:9]
	v_lshlrev_b64 v[10:11], 12, v[10:11]
	v_lshl_add_u64 v[4:5], v[2:3], 0, v[36:37]
	v_lshl_add_u64 v[6:7], v[2:3], 0, v[6:7]
	v_lshlrev_b64 v[32:33], 12, v[0:1]
	v_add_u32_e32 v0, s1, v51
	s_waitcnt lgkmcnt(0)
	v_mov_b32_e32 v13, v1
	v_mov_b32_e32 v27, v1
	v_or_b32_e32 v52, s21, v15
	v_or_b32_e32 v54, s9, v15
	v_or_b32_e32 v55, s10, v14
	v_add_u32_e32 v12, s5, v48
	v_add_u32_e32 v26, s5, v50
	v_lshl_add_u64 v[8:9], v[2:3], 0, v[8:9]
	v_lshl_add_u64 v[10:11], v[2:3], 0, v[10:11]
	global_load_dword v60, v[4:5], off nt
	global_load_dword v61, v[8:9], off nt
	global_load_dword v62, v[6:7], off nt
	global_load_dword v63, v[10:11], off nt
	v_lshlrev_b64 v[6:7], 12, v[0:1]
	v_add_u32_e32 v0, s1, v53
	v_mov_b32_e32 v29, v1
	v_mov_b32_e32 v31, v1
	v_add_u32_e32 v28, s5, v52
	v_add_u32_e32 v30, s5, v54
	v_lshlrev_b64 v[12:13], 12, v[12:13]
	v_lshlrev_b64 v[26:27], 12, v[26:27]
	v_lshl_add_u64 v[4:5], v[2:3], 0, v[32:33]
	v_lshl_add_u64 v[6:7], v[2:3], 0, v[6:7]
	v_lshlrev_b64 v[8:9], 12, v[0:1]
	v_add_u32_e32 v0, s1, v55
	v_lshlrev_b64 v[28:29], 12, v[28:29]
	v_lshlrev_b64 v[30:31], 12, v[30:31]
	v_lshl_add_u64 v[12:13], v[2:3], 0, v[12:13]
	v_lshl_add_u64 v[26:27], v[2:3], 0, v[26:27]
	global_load_dword v64, v[4:5], off nt
	global_load_dword v65, v[12:13], off nt
	global_load_dword v66, v[6:7], off nt
	global_load_dword v67, v[26:27], off nt
	v_lshl_add_u64 v[4:5], v[2:3], 0, v[8:9]
	v_lshlrev_b64 v[6:7], 12, v[0:1]
	v_lshl_add_u64 v[28:29], v[2:3], 0, v[28:29]
	v_lshl_add_u64 v[30:31], v[2:3], 0, v[30:31]
	v_lshl_add_u64 v[6:7], v[2:3], 0, v[6:7]
	global_load_dword v0, v[4:5], off nt
	global_load_dword v68, v[28:29], off nt
	global_load_dword v69, v[6:7], off nt
	global_load_dword v70, v[30:31], off nt
	s_add_i32 s7, s7, 16
	s_add_i32 s4, s4, 16
	s_add_i32 s8, s8, -16
	v_mad_u64_u32 v[4:5], s[10:11], v41, s26, v[18:19]
	s_cmp_lg_u32 s8, 0
	v_mad_u64_u32 v[6:7], s[10:11], v40, s26, v[18:19]
	v_mad_u64_u32 v[8:9], s[10:11], v43, s26, v[18:19]
	v_mad_u64_u32 v[10:11], s[10:11], v42, s26, v[18:19]
	v_mad_u64_u32 v[12:13], s[10:11], v45, s26, v[18:19]
	v_mad_u64_u32 v[26:27], s[10:11], v44, s26, v[18:19]
	v_mad_u64_u32 v[28:29], s[10:11], v47, s26, v[18:19]
	v_mad_u64_u32 v[30:31], s[10:11], v46, s26, v[18:19]
	v_mad_u64_u32 v[32:33], s[10:11], v49, s26, v[18:19]
	v_mad_u64_u32 v[34:35], s[10:11], v48, s26, v[18:19]
	v_mad_u64_u32 v[36:37], s[10:11], v51, s26, v[18:19]
	v_mad_u64_u32 v[40:41], s[10:11], v50, s26, v[18:19]
	v_mad_u64_u32 v[42:43], s[10:11], v53, s26, v[18:19]
	v_mad_u64_u32 v[44:45], s[10:11], v52, s26, v[18:19]
	v_mad_u64_u32 v[46:47], s[10:11], v55, s26, v[18:19]
	v_mad_u64_u32 v[48:49], s[10:11], v54, s26, v[18:19]
	s_waitcnt vmcnt(15)
	ds_write_b32 v4, v56
	s_waitcnt vmcnt(14)
	ds_write_b32 v6, v57
	s_waitcnt vmcnt(13)
	ds_write_b32 v8, v58
	s_waitcnt vmcnt(12)
	ds_write_b32 v10, v59
	s_waitcnt vmcnt(11)
	ds_write_b32 v12, v60
	s_waitcnt vmcnt(10)
	ds_write_b32 v26, v61
	s_waitcnt vmcnt(9)
	ds_write_b32 v28, v62
	s_waitcnt vmcnt(8)
	ds_write_b32 v30, v63
	s_waitcnt vmcnt(7)
	ds_write_b32 v32, v64
	s_waitcnt vmcnt(6)
	ds_write_b32 v34, v65
	s_waitcnt vmcnt(5)
	ds_write_b32 v36, v66
	s_waitcnt vmcnt(4)
	ds_write_b32 v40, v67
	s_waitcnt vmcnt(3)
	ds_write_b32 v42, v0
	s_waitcnt vmcnt(2)
	ds_write_b32 v44, v68
	s_waitcnt vmcnt(1)
	ds_write_b32 v46, v69
	s_waitcnt vmcnt(0)
	ds_write_b32 v48, v70
	s_cbranch_scc1 .LBB0_1486
; #define LAS __attribute__((address_space(3)))
; __device__ __forceinline__ v4u pack8(const float (&f)[8]) { v4u w; w.x = cvt_pk_bf16(f[0], f[1]); w.y = cvt_pk_bf16(f[2], f[3]); w.z = cvt_pk_bf16(f[4], f[5]); w.w = cvt_pk_bf16(f[6], f[7]); return w; }
; __device__ __forceinline__ void tr_item(const float* __restrict__ W, int ldw, int k0, int n0, bf16* __restrict__ WT, int ldt, int drow, const float* __restrict__ mu, LAS float* scr, int lane, const float* __restrict__ gs = nullptr) {
;     ...
;     for (int j = 0; j < 4; ++j) {
;         const int n = (lane >> 3) + 8 * j; const LAS float* s = scr + (8 * c) * 33 + n;
;         float f[8];
; #pragma unroll
;         for (int e = 0; e < 8; ++e) f[e] = s[e * 33];
;         bf16* dp = WT + (size_t)(drow + n) * ldt + k0 + 8 * c;
;         if (mu) {
;             float f1[8], f2[8];
; #pragma unroll
;             for (int e = 0; e < 8; ++e) { f1[e] = f[e] * (1.f - mv[e]); f2[e] = f[e] * mv[e]; }
;             *(v4u*)dp = pack8(f1); *(v4u*)(dp + 1024) = pack8(f2);
;         } else { if (gs) {
; #pragma unroll
;             for (int e = 0; e < 8; ++e) f[e] *= mv[e]; }
;             *(v4u*)dp = pack8(f); }
	s_lshl_b64 s[4:5], s[94:95], 22
	v_readlane_b32 s7, v252, 20
	s_add_u32 s4, s7, s4
	v_readlane_b32 s7, v252, 21
	s_addc_u32 s5, s7, s5
	s_lshl_b32 s1, s1, 1
	s_waitcnt lgkmcnt(0)
	s_add_u32 s4, s4, s1
	s_addc_u32 s5, s5, 0
	v_lshlrev_b32_e32 v0, 1, v20
	ds_read2_b32 v[8:9], v19 offset0:33 offset1:41
	ds_read2_b32 v[10:11], v19 offset1:8
	ds_read2_b32 v[12:13], v19 offset0:66 offset1:74
	ds_read2_b32 v[26:27], v19 offset0:99 offset1:107
	ds_read2_b32 v[28:29], v19 offset0:132 offset1:140
	ds_read2_b32 v[30:31], v19 offset0:165 offset1:173
	ds_read2_b32 v[32:33], v19 offset0:198 offset1:206
	ds_read2_b32 v[34:35], v19 offset0:231 offset1:239
	v_lshl_add_u64 v[6:7], s[4:5], 0, v[0:1]
	v_or_b32_e32 v0, s0, v17
	v_lshlrev_b32_e32 v0, 12, v0
	v_lshl_add_u64 v[36:37], v[6:7], 0, v[0:1]
	v_or_b32_e32 v0, s0, v21
	v_lshlrev_b32_e32 v0, 12, v0
	s_waitcnt lgkmcnt(6)
	v_cvt_pk_bf16_f32 v2, v10, v8
	s_waitcnt lgkmcnt(4)
	v_cvt_pk_bf16_f32 v3, v12, v26
	s_waitcnt lgkmcnt(2)
	v_cvt_pk_bf16_f32 v4, v28, v30
	s_waitcnt lgkmcnt(0)
	v_cvt_pk_bf16_f32 v5, v32, v34
	global_store_dwordx4 v[36:37], v[2:5], off nt
	v_lshl_add_u64 v[36:37], v[6:7], 0, v[0:1]
	v_or_b32_e32 v0, s0, v38
	v_cvt_pk_bf16_f32 v2, v11, v9
	v_cvt_pk_bf16_f32 v3, v13, v27
	v_cvt_pk_bf16_f32 v4, v29, v31
	v_cvt_pk_bf16_f32 v5, v33, v35
	global_store_dwordx4 v[36:37], v[2:5], off nt
	ds_read2_b32 v[8:9], v19 offset0:16 offset1:24
	ds_read2_b32 v[10:11], v19 offset0:49 offset1:57
	ds_read2_b32 v[12:13], v19 offset0:82 offset1:90
	ds_read2_b32 v[26:27], v19 offset0:115 offset1:123
	ds_read2_b32 v[28:29], v19 offset0:148 offset1:156
	ds_read2_b32 v[30:31], v19 offset0:181 offset1:189
	ds_read2_b32 v[32:33], v19 offset0:214 offset1:222
	ds_read2_b32 v[34:35], v19 offset0:247 offset1:255
	v_lshlrev_b32_e32 v0, 12, v0
	v_lshl_add_u64 v[36:37], v[6:7], 0, v[0:1]
	v_or_b32_e32 v0, s0, v39
	v_lshlrev_b32_e32 v0, 12, v0
	s_waitcnt lgkmcnt(6)
	v_cvt_pk_bf16_f32 v2, v8, v10
	s_waitcnt lgkmcnt(4)
	v_cvt_pk_bf16_f32 v3, v12, v26
	s_waitcnt lgkmcnt(2)
	v_cvt_pk_bf16_f32 v4, v28, v30
	s_waitcnt lgkmcnt(0)
	v_cvt_pk_bf16_f32 v5, v32, v34
	v_lshl_add_u64 v[6:7], v[6:7], 0, v[0:1]
	global_store_dwordx4 v[36:37], v[2:5], off nt
	s_nop 1
	v_cvt_pk_bf16_f32 v2, v9, v11
	v_cvt_pk_bf16_f32 v3, v13, v27
	v_cvt_pk_bf16_f32 v4, v29, v31
	v_cvt_pk_bf16_f32 v5, v33, v35
	global_store_dwordx4 v[6:7], v[2:5], off nt
	s_waitcnt lgkmcnt(0)

; __device__ __forceinline__ void tr_item(const float* __restrict__ W, int ldw, int k0, int n0, bf16* __restrict__ WT, int ldt, int drow, const float* __restrict__ mu, LAS float* scr, int lane, const float* __restrict__ gs = nullptr) {
; #pragma unroll 8
;     for (int i = 0; i < 32; ++i) { const int kk = 2 * i + (lane >> 5); scr[kk * 33 + (lane & 31)] = W[(size_t)(k0 + kk) * ldw + n0 + (lane & 31)]; }
;     asm volatile("s_waitcnt lgkmcnt(0)" ::: "memory");
;     const int c = lane & 7;
;     float mv[8];
;     if (mu) {
; #pragma unroll
;         for (int e = 0; e < 8; ++e) mv[e] = mu[k0 + 8 * c + e];
;     } else if (gs) {
; #pragma unroll
;         for (int e = 0; e < 8; ++e) mv[e] = gs[k0 + 8 * c + e];
.LBB0_1490:
	s_lshl_b32 s10, s7, 1
	s_lshl_b32 s11, s8, 1
	v_or_b32_e32 v0, s10, v15
	v_or_b32_e32 v50, s11, v14
	s_add_i32 s12, s10, 4
	s_add_i32 s13, s11, 4
	s_add_i32 s14, s10, 8
	s_add_i32 s15, s11, 8
	s_add_i32 s16, s10, 12
	s_add_i32 s17, s11, 12
	s_add_i32 s18, s10, 16
	s_add_i32 s19, s11, 16
	s_add_i32 s20, s10, 20
	s_add_i32 s21, s11, 20
	s_add_i32 s22, s10, 24
	s_add_i32 s23, s11, 24
	s_add_i32 s10, s10, 28
	s_add_i32 s11, s11, 28
	v_add_u32_e32 v4, s4, v50
	v_or_b32_e32 v51, s12, v15
	v_or_b32_e32 v52, s13, v14
	v_or_b32_e32 v53, s14, v15
	v_or_b32_e32 v54, s15, v14
	v_or_b32_e32 v55, s16, v15
	v_or_b32_e32 v56, s17, v14
	v_or_b32_e32 v57, s18, v15
	v_or_b32_e32 v58, s19, v14
	v_or_b32_e32 v59, s20, v15
	v_or_b32_e32 v60, s21, v14
	v_or_b32_e32 v61, s22, v15
	v_or_b32_e32 v62, s23, v14
	v_or_b32_e32 v63, s10, v15
	v_or_b32_e32 v64, s11, v14
	v_add_u32_e32 v6, s1, v0
	v_mad_i64_i32 v[4:5], s[10:11], v4, s33, v[2:3]
	v_add_u32_e32 v10, s1, v51
	v_add_u32_e32 v8, s4, v52
	v_add_u32_e32 v26, s1, v53
	s_waitcnt lgkmcnt(0)
	v_add_u32_e32 v12, s4, v54
	v_add_u32_e32 v30, s1, v55
	v_add_u32_e32 v28, s4, v56
	v_add_u32_e32 v34, s1, v57
	v_add_u32_e32 v32, s4, v58
	v_add_u32_e32 v40, s1, v59
	v_add_u32_e32 v36, s4, v60
	v_add_u32_e32 v44, s1, v61
	v_add_u32_e32 v42, s4, v62
	v_add_u32_e32 v48, s1, v63
	v_add_u32_e32 v46, s4, v64
	v_mad_i64_i32 v[6:7], s[10:11], v6, s33, v[2:3]
	v_mad_i64_i32 v[8:9], s[10:11], v8, s33, v[2:3]
	v_mad_i64_i32 v[10:11], s[10:11], v10, s33, v[2:3]
	v_mad_i64_i32 v[12:13], s[10:11], v12, s33, v[2:3]
	v_mad_i64_i32 v[26:27], s[10:11], v26, s33, v[2:3]
	v_mad_i64_i32 v[28:29], s[10:11], v28, s33, v[2:3]
	v_mad_i64_i32 v[30:31], s[10:11], v30, s33, v[2:3]
	v_mad_i64_i32 v[32:33], s[10:11], v32, s33, v[2:3]
	v_mad_i64_i32 v[34:35], s[10:11], v34, s33, v[2:3]
	v_mad_i64_i32 v[36:37], s[10:11], v36, s33, v[2:3]
	v_mad_i64_i32 v[40:41], s[10:11], v40, s33, v[2:3]
	v_mad_i64_i32 v[42:43], s[10:11], v42, s33, v[2:3]
	v_mad_i64_i32 v[44:45], s[10:11], v44, s33, v[2:3]
	v_mad_i64_i32 v[46:47], s[10:11], v46, s33, v[2:3]
	v_mad_i64_i32 v[48:49], s[10:11], v48, s33, v[2:3]
	global_load_dword v65, v[4:5], off nt
	global_load_dword v66, v[6:7], off nt
	global_load_dword v67, v[8:9], off nt
	global_load_dword v68, v[10:11], off nt
	global_load_dword v69, v[12:13], off nt
	global_load_dword v70, v[26:27], off nt
	global_load_dword v71, v[28:29], off nt
	global_load_dword v72, v[30:31], off nt
	global_load_dword v73, v[32:33], off nt
	global_load_dword v74, v[34:35], off nt
	global_load_dword v75, v[36:37], off nt
	global_load_dword v76, v[40:41], off nt
	global_load_dword v77, v[42:43], off nt
	global_load_dword v78, v[44:45], off nt
	global_load_dword v79, v[46:47], off nt
	global_load_dword v80, v[48:49], off nt
	s_add_i32 s8, s8, 16
	s_add_i32 s7, s7, 16
	s_add_i32 s9, s9, -16
	v_mad_u64_u32 v[4:5], s[10:11], v50, s26, v[18:19]
	s_cmp_lg_u32 s9, 0
	v_mad_u64_u32 v[6:7], s[10:11], v0, s26, v[18:19]
	v_mad_u64_u32 v[8:9], s[10:11], v52, s26, v[18:19]
	v_mad_u64_u32 v[10:11], s[10:11], v51, s26, v[18:19]
	v_mad_u64_u32 v[12:13], s[10:11], v54, s26, v[18:19]
	v_mad_u64_u32 v[26:27], s[10:11], v53, s26, v[18:19]
	v_mad_u64_u32 v[28:29], s[10:11], v56, s26, v[18:19]
	v_mad_u64_u32 v[30:31], s[10:11], v55, s26, v[18:19]
	v_mad_u64_u32 v[32:33], s[10:11], v58, s26, v[18:19]
	v_mad_u64_u32 v[34:35], s[10:11], v57, s26, v[18:19]
	v_mad_u64_u32 v[36:37], s[10:11], v60, s26, v[18:19]
	v_mad_u64_u32 v[40:41], s[10:11], v59, s26, v[18:19]
	v_mad_u64_u32 v[42:43], s[10:11], v62, s26, v[18:19]
	v_mad_u64_u32 v[44:45], s[10:11], v61, s26, v[18:19]
	v_mad_u64_u32 v[46:47], s[10:11], v64, s26, v[18:19]
	v_mad_u64_u32 v[48:49], s[10:11], v63, s26, v[18:19]
	s_waitcnt vmcnt(15)
	ds_write_b32 v4, v65
	s_waitcnt vmcnt(14)
	ds_write_b32 v6, v66
	s_waitcnt vmcnt(13)
	ds_write_b32 v8, v67
	s_waitcnt vmcnt(12)
	ds_write_b32 v10, v68
	s_waitcnt vmcnt(11)
	ds_write_b32 v12, v69
	s_waitcnt vmcnt(10)
	ds_write_b32 v26, v70
	s_waitcnt vmcnt(9)
	ds_write_b32 v28, v71
	s_waitcnt vmcnt(8)
	ds_write_b32 v30, v72
	s_waitcnt vmcnt(7)
	ds_write_b32 v32, v73
	s_waitcnt vmcnt(6)
	ds_write_b32 v34, v74
	s_waitcnt vmcnt(5)
	ds_write_b32 v36, v75
	s_waitcnt vmcnt(4)
	ds_write_b32 v40, v76
	s_waitcnt vmcnt(3)
	ds_write_b32 v42, v77
	s_waitcnt vmcnt(2)
	ds_write_b32 v44, v78
	s_waitcnt vmcnt(1)
	ds_write_b32 v46, v79
	s_waitcnt vmcnt(0)
	ds_write_b32 v48, v80
	s_cbranch_scc1 .LBB0_1490
	s_waitcnt lgkmcnt(0)
	v_readlane_b32 s8, v253, 36
	v_readlane_b32 s9, v253, 37
	v_mov_b32_e32 v4, 0
	s_andn2_b64 vcc, exec, s[8:9]
	v_mov_b32_e32 v5, 0
	v_mov_b32_e32 v6, 0
	v_mov_b32_e32 v7, 0
	v_mov_b32_e32 v8, 0
	v_mov_b32_e32 v9, 0
	v_mov_b32_e32 v2, 0
	v_mov_b32_e32 v3, 0
	v_mov_b32_e32 v10, 0
	v_mov_b32_e32 v11, 0
	s_cbranch_vccnz .LBB0_1414
	s_lshl_b32 s8, s5, 1
	s_ashr_i32 s9, s8, 31
	v_readlane_b32 s68, v253, 20
	s_lshl_b64 s[8:9], s[8:9], 12
	v_readlane_b32 s82, v253, 34
	v_readlane_b32 s83, v253, 35
	s_add_u32 s8, s82, s8
	v_or_b32_e32 v2, s4, v20
	s_addc_u32 s9, s83, s9
	v_ashrrev_i32_e32 v3, 31, v2
	v_lshl_add_u64 v[6:7], v[2:3], 2, s[8:9]
	global_load_dwordx4 v[2:5], v[6:7], off offset:16
	s_nop 0
	global_load_dwordx4 v[6:9], v[6:7], off
	v_readlane_b32 s69, v253, 21
	v_readlane_b32 s70, v253, 22
	v_readlane_b32 s71, v253, 23
	v_readlane_b32 s72, v253, 24
	v_readlane_b32 s73, v253, 25
	v_readlane_b32 s74, v253, 26
	v_readlane_b32 s75, v253, 27
	v_readlane_b32 s76, v253, 28
	v_readlane_b32 s77, v253, 29
	v_readlane_b32 s78, v253, 30
	v_readlane_b32 s79, v253, 31
	v_readlane_b32 s80, v253, 32
	v_readlane_b32 s81, v253, 33
	s_waitcnt vmcnt(1)
	v_mov_b32_e32 v10, v4
	v_mov_b32_e32 v11, v5
	s_branch .LBB0_1414
